# layer-1 workspace re-layout (PM above the FFN activations) so every mid-pipeline seam is XCD-local; one full grid barrier left (after weight prep)
# speedup vs baseline: 1.0520x; 1.0034x over previous
; #define LAS __attribute__((address_space(3)))
; DI unsigned xb_add(unsigned* p, unsigned v) { return __hip_atomic_fetch_add(p, v, __ATOMIC_RELAXED, __HIP_MEMORY_SCOPE_AGENT); }
; DI unsigned xb_xcc_id() { return (unsigned)__builtin_amdgcn_s_getreg((3 << 11) | 20) & 0xFu; }
; #define PG8_LAS __attribute__((address_space(3)))
; DI XcdBarrier xcd_barrier_post(unsigned* bar, volatile LAS unsigned* st) {
;   XcdBarrier b; b.bar = bar; b.x = xb_xcc_id(); b.st = st;
;   if (threadIdx.x == 0) (void)xb_add(&bar[XB_XCNT(b.x)], 1u);
;   return b;
; }
; __global__ void __launch_bounds__(NTHREADS, 2) fwd_megakernel(Params p) {
;   extern __shared__ __attribute__((aligned(16))) char smem[];
;   cg::grid_group grid = cg::this_grid();
;   char* ws = p.ws;
;   int toff = 0;
;   __shared__ uint4 xb_words;
;   if (threadIdx.x == 0) xb_words = make_uint4(0u, 0u, 0u, 0u);
;   __syncthreads();
;   const XcdBarrier xb = xcd_barrier_post((unsigned*)(ws + O_BAR), (volatile LAS unsigned*)&xb_words);
;   PG8_LAS unsigned char* lds = (PG8_LAS unsigned char*)smem;
;   float* ps1 = (float*)(ws + O_PS1); float* ps2 = (float*)(ws + O_PS2);
_Z14fwd_megakernel6Params:
	s_load_dwordx2 s[88:89], s[0:1], 0xb0
	s_add_u32 s8, s0, 0xb0
	s_addc_u32 s9, s1, 0
	s_mov_b32 s42, s2
	v_mov_b32_e32 v2, 0
	s_waitcnt lgkmcnt(0)
	s_cmp_lt_u32 s2, s88
	s_cselect_b32 s2, 12, 18
	s_add_u32 s2, s8, s2
	s_addc_u32 s3, s9, 0
	global_load_dword v1, v2, s[0:1] offset:190
	global_load_ushort v3, v2, s[2:3]
	s_load_dwordx4 s[84:87], s[0:1], 0xa0
	s_load_dwordx8 s[76:83], s[0:1], 0x80
	v_and_b32_e32 v212, 0x3ff, v0
	v_cmp_eq_u32_e64 s[36:37], 0, v212
	s_waitcnt vmcnt(1)
	v_readfirstlane_b32 s2, v1
	s_nop 1
	v_writelane_b32 v254, s2, 0
	s_waitcnt vmcnt(0)
	v_readfirstlane_b32 s2, v3
	s_nop 1
	v_writelane_b32 v254, s2, 2
	s_and_saveexec_b64 s[4:5], s[36:37]
	v_mov_b32_e32 v3, v2
	v_mov_b32_e32 v4, v2
	v_mov_b32_e32 v5, v2
	ds_write_b128 v2, v[2:5] offset:256
	s_or_b64 exec, exec, s[4:5]
	s_load_dword s2, s[0:1], 0xb8
	s_load_dwordx16 s[44:59], s[0:1], 0x0
	s_waitcnt lgkmcnt(0)
	s_barrier
	v_writelane_b32 v254, s2, 4
	s_add_u32 s92, s86, 0xbfa0000
	s_getreg_b32 s2, hwreg(HW_REG_XCC_ID, 0, 4)
	s_addc_u32 s93, s87, 0
	s_add_u32 s98, s86, 0x17fa4000
	s_addc_u32 s99, s87, 0
	s_and_b32 s27, s2, 15
	s_and_saveexec_b64 s[4:5], s[36:37]
	s_cbranch_execz .LBB0_5
	s_mov_b64 s[6:7], exec
	v_mbcnt_lo_u32_b32 v1, s6, 0
	v_mbcnt_hi_u32_b32 v1, s7, v1
	v_cmp_eq_u32_e32 vcc, 0, v1
	s_and_b64 s[2:3], exec, vcc
	s_mov_b64 exec, s[2:3]
	s_cbranch_execz .LBB0_5
	s_and_b32 s2, s42, 7
	s_lshl_b32 s2, s2, 2
	s_lshl_b32 s3, 1, s27
	v_mov_b32_e32 v1, s2
	v_mov_b32_e32 v2, s3
	global_atomic_or v2, v1, v2, s[92:93] sc0
	s_waitcnt vmcnt(0)
	s_lshl_b32 s2, s27, 8
	s_bcnt1_i32_b64 s3, s[6:7]
	v_mov_b32_e32 v1, s2
	v_mov_b32_e32 v2, s3
	global_atomic_add v1, v2, s[92:93] offset:1024

; DI unsigned xb_ld(unsigned* p) { return __hip_atomic_load(p, __ATOMIC_RELAXED, __HIP_MEMORY_SCOPE_AGENT); }
; DI unsigned xb_add(unsigned* p, unsigned v) { return __hip_atomic_fetch_add(p, v, __ATOMIC_RELAXED, __HIP_MEMORY_SCOPE_AGENT); }
; #define XB_SPIN(cond, bar) do { unsigned _sp = 0; while (cond) { __builtin_amdgcn_s_sleep(1); \
;     if ((++_sp & 255u) == 0u) { if (xb_ld(&(bar)[XB_TMO])) break; if (_sp > XB_SPIN_CAP) { atomicAdd(&(bar)[XB_TMO], 1u); break; } } } } while (0)
; DI void xcd_barrier(const XcdBarrier& b) {
;     ...
;     if (old + 1u == (gen + 1u) * nloc) {
;       __builtin_amdgcn_fence(__ATOMIC_RELEASE, "agent");
;       asm volatile("s_waitcnt vmcnt(0)" ::: "memory");
;       const unsigned og = xb_add(&bar[XB_TOP], 1u);
;       const unsigned tg = og / nx;
;       if (og + 1u == (tg + 1u) * nx) xb_add(&bar[XB_TOPGEN], 1u);
;       else XB_SPIN(xb_ld(&bar[XB_TOPGEN]) == tg, bar);
.LBB0_776:
	s_andn2_saveexec_b64 s[2:3], s[8:9]
	s_cbranch_execz .LBB0_796
	s_mov_b64 s[8:9], exec
	v_mov_b32_e32 v255, 0
	ds_read_b32 v255, v255 offset:264
	s_waitcnt lgkmcnt(0)
	v_cmp_ne_u32_e32 vcc, 0, v255
	s_cbranch_vccz .Lxl_full_6
	v_mov_b32_e32 v255, 0xbfa0210
	v_mov_b32_e32 v0, 1
	global_atomic_add v255, v0, s[86:87]
	s_branch .LBB0_793
.Lxl_full_6:
	buffer_wbl2 sc1
	s_waitcnt lgkmcnt(0)
	s_waitcnt vmcnt(0)
	v_mbcnt_lo_u32_b32 v0, s8, 0
	v_mbcnt_hi_u32_b32 v0, s9, v0
	v_cmp_eq_u32_e32 vcc, 0, v0
	s_and_saveexec_b64 s[10:11], vcc
	s_cbranch_execz .LBB0_779
	s_bcnt1_i32_b64 s2, s[8:9]
	v_mov_b32_e32 v2, 0xbfa3000
	v_mov_b32_e32 v3, s2
	global_atomic_add v2, v2, v3, s[86:87] offset:1024 sc0
.LBB0_779:
	s_or_b64 exec, exec, s[10:11]
	v_cvt_f32_u32_e32 v3, v1
	s_waitcnt vmcnt(0)
	v_readfirstlane_b32 s2, v2
	s_add_u32 s10, s86, 0xbfa3500
	s_addc_u32 s11, s87, 0
	v_rcp_iflag_f32_e32 v3, v3
	v_add_u32_e32 v0, s2, v0
	v_add_u32_e32 v4, 1, v0
	s_mov_b64 s[12:13], -1
	v_mul_f32_e32 v2, 0x4f7ffffe, v3
	v_cvt_u32_f32_e32 v2, v2
	v_sub_u32_e32 v3, 0, v1
	v_mul_lo_u32 v3, v3, v2
	v_mul_hi_u32 v3, v2, v3
	v_add_u32_e32 v2, v2, v3
	v_mul_hi_u32 v2, v0, v2
	v_mul_lo_u32 v3, v2, v1
	v_sub_u32_e32 v0, v0, v3
	v_add_u32_e32 v5, 1, v2
	v_cmp_ge_u32_e32 vcc, v0, v1
	v_sub_u32_e32 v3, v0, v1
	s_nop 0
	v_cndmask_b32_e32 v2, v2, v5, vcc
	v_cndmask_b32_e32 v0, v0, v3, vcc
	v_add_u32_e32 v3, 1, v2
	v_cmp_ge_u32_e32 vcc, v0, v1
	s_nop 1
	v_cndmask_b32_e32 v2, v2, v3, vcc
	v_mul_lo_u32 v0, v1, v2
	v_add_u32_e32 v0, v0, v1
	v_cmp_ne_u32_e32 vcc, v4, v0
	v_mov_b64_e32 v[0:1], s[10:11]
	s_and_saveexec_b64 s[8:9], vcc
	s_cbranch_execz .LBB0_791
	v_mov_b32_e32 v0, 0
	global_load_dword v1, v0, s[10:11] sc1
	s_mov_b64 s[20:21], 0
	s_waitcnt vmcnt(0)
	v_cmp_eq_u32_e32 vcc, v1, v2
	s_and_saveexec_b64 s[14:15], vcc
	s_cbranch_execz .LBB0_790
	s_add_u32 s12, s86, 0xbfa0200
	s_addc_u32 s13, s87, 0
	s_mov_b32 s2, 1
	s_branch .LBB0_783

; DI unsigned pack2(float a, float b) { bf2_t v = __builtin_convertvector((f32x2){a, b}, bf2_t); return __builtin_bit_cast(unsigned, v); }
; DI void rows_rstd(float (&rs)[2][4], const float* ps, const Unit& u, int wr, int fr, int fq, int p_lo, int p_hi, float inv_dim) {
;   f32x4 pv[2][4];
; #pragma unroll
;   for (int ai = 0; ai < 2; ++ai)
; #pragma unroll
;     for (int m = 0; m < 4; ++m) pv[ai][m] = *(const f32x4*)(ps + (size_t)(u.pm * BM + ai * HALF + wr * 64 + m * 16 + fr) * 16 + 4 * fq);
;   const bool use = (4 * fq >= p_lo) && (4 * fq < p_hi);
; #pragma unroll
;   for (int ai = 0; ai < 2; ++ai)
; #pragma unroll
;     for (int m = 0; m < 4; ++m) {
;       float s = use ? (pv[ai][m][0] + pv[ai][m][1]) + (pv[ai][m][2] + pv[ai][m][3]) : 0.f;
;       s += __shfl_xor(s, 16); s += __shfl_xor(s, 32);
;       rs[ai][m] = rsqrtf(s * inv_dim + EPS);
;     }
;   DI void operator()(const f32x4 (&acc)[2][2][4][2], const Unit& u, int wr, int wc, int fr, int fq) const {
;     float rsv[2][4];
;     if (ps_in) rows_rstd(rsv, ps_in, u, wr, fr, fq, p_lo, p_hi, inv_dim);
; #pragma unroll
;     for (int ai = 0; ai < 2; ++ai)
; #pragma unroll
;       for (int m = 0; m < 4; ++m) {
;         const int row = u.pm * BM + ai * HALF + wr * 64 + m * 16 + fr;
;         const float rs = ps_in ? rsv[ai][m] : 1.f;
;         float ssum = 0.f;
; #pragma unroll
;         for (int bj = 0; bj < 2; ++bj) {
;           const int c0 = u.pn * BM + bj * HALF + wc * 32 + 8 * fq;
;           const f32x4 v0 = acc[ai][bj][m][0] * rs, v1 = acc[ai][bj][m][1] * rs;
;           if (PSOUT) ssum += (v0[0] * v0[0] + v0[1] * v0[1]) + (v0[2] * v0[2] + v0[3] * v0[3]) + (v1[0] * v1[0] + v1[1] * v1[1]) + (v1[2] * v1[2] + v1[3] * v1[3]);
;           u32x4 w; w.x = pack2(v0[0], v0[1]); w.y = pack2(v0[2], v0[3]); w.z = pack2(v1[0], v1[1]); w.w = pack2(v1[2], v1[3]);
;           if (EMODE == EM_KVUP) {
;             const int hh = c0 >> 7, j = c0 & 127;
;             if (j < 64) *(u32x4*)(O + (size_t)row * 1152 + hh * 96 + j) = w; else *(u32x4*)(O2 + (size_t)row * 768 + hh * 64 + (j - 64)) = w;
;           } else {
;             if (c0 < ncols) *(u32x4*)(O + (size_t)row * ldo + c0) = w;
;           }
;         }
;         if (PSOUT) { ssum += __shfl_xor(ssum, 16); ssum += __shfl_xor(ssum, 32); if (fq == 0 && u.pn < 4) ps_out[(size_t)row * 16 + u.pn * 4 + wc] = ssum; }
.LBB0_810:
	v_lshl_add_u32 v184, s8, 8, v143
	v_or_b32_e32 v180, 16, v184
	v_ashrrev_i32_e32 v181, 31, v180
	v_or_b32_e32 v172, 32, v184
	v_lshlrev_b64 v[178:179], 6, v[180:181]
	v_ashrrev_i32_e32 v173, 31, v172
	v_ashrrev_i32_e32 v185, 31, v184
	v_lshl_add_u64 v[144:145], v[136:137], 0, v[178:179]
	v_lshlrev_b64 v[170:171], 6, v[172:173]
	v_lshlrev_b64 v[182:183], 6, v[184:185]
	v_lshl_add_u64 v[146:147], v[136:137], 0, v[170:171]
	global_load_dwordx4 v[162:165], v[144:145], off
	global_load_dwordx4 v[174:177], v[146:147], off
	v_lshl_add_u64 v[144:145], v[136:137], 0, v[182:183]
	global_load_dwordx4 v[186:189], v[144:145], off
	v_or_b32_e32 v168, 48, v184
	v_ashrrev_i32_e32 v169, 31, v168
	v_add_u32_e32 v160, 0x80, v184
	v_add_u32_e32 v156, 0x90, v184
	v_lshlrev_b64 v[166:167], 6, v[168:169]
	v_ashrrev_i32_e32 v161, 31, v160
	v_ashrrev_i32_e32 v157, 31, v156
	v_lshl_add_u64 v[144:145], v[136:137], 0, v[166:167]
	v_lshlrev_b64 v[158:159], 6, v[160:161]
	v_lshlrev_b64 v[154:155], 6, v[156:157]
	v_lshl_add_u64 v[146:147], v[136:137], 0, v[158:159]
	global_load_dwordx4 v[190:193], v[144:145], off
	global_load_dwordx4 v[202:205], v[146:147], off
	v_lshl_add_u64 v[144:145], v[136:137], 0, v[154:155]
	global_load_dwordx4 v[206:209], v[144:145], off
	v_add_u32_e32 v150, 0xa0, v184
	v_ashrrev_i32_e32 v151, 31, v150
	v_lshlrev_b64 v[148:149], 6, v[150:151]
	v_add_u32_e32 v146, 0xb0, v184
	v_lshl_add_u64 v[144:145], v[136:137], 0, v[148:149]
	v_ashrrev_i32_e32 v147, 31, v146
	global_load_dwordx4 v[214:217], v[144:145], off
	v_lshlrev_b64 v[144:145], 6, v[146:147]
	v_lshl_add_u64 v[152:153], v[136:137], 0, v[144:145]
	global_load_dwordx4 v[218:221], v[152:153], off
	v_and_b32_e32 v151, 64, v198
	v_xor_b32_e32 v147, 32, v198
	v_add_u32_e32 v151, 64, v151
	v_xor_b32_e32 v152, 16, v198
	v_cmp_lt_i32_e32 vcc, v147, v151
	s_waitcnt vmcnt(0)
	v_mov_b32_e32 v153, v188
	v_cndmask_b32_e32 v147, v198, v147, vcc
	v_cmp_lt_i32_e32 vcc, v152, v151
	v_mov_b32_e32 v188, v163
	v_mov_b32_e32 v163, v165
	v_cndmask_b32_e32 v151, v198, v152, vcc
	v_mov_b32_e32 v152, v187
	v_mov_b32_e32 v187, v189
	v_mov_b32_e32 v189, v164
	v_pk_add_f32 v[152:153], v[152:153], v[186:187]
	v_pk_add_f32 v[162:163], v[188:189], v[162:163]
	v_mov_b32_e32 v189, v152
	v_mov_b32_e32 v188, v162
	v_mov_b32_e32 v152, v163
	v_lshlrev_b32_e32 v151, 2, v151
	v_pk_add_f32 v[152:153], v[188:189], v[152:153]
	ds_bpermute_b32 v189, v151, v153
	ds_bpermute_b32 v188, v151, v152
	v_mov_b32_e32 v164, v175
	v_mov_b32_e32 v165, v176
	v_mov_b32_e32 v175, v177
	v_mov_b32_e32 v176, v191
	v_mov_b32_e32 v177, v192
	v_mov_b32_e32 v191, v193
	v_mov_b32_e32 v192, v203
	v_mov_b32_e32 v193, v204
	v_mov_b32_e32 v203, v205
	v_mov_b32_e32 v204, v207
	v_mov_b32_e32 v205, v208
	v_mov_b32_e32 v207, v209
	v_pk_add_f32 v[164:165], v[164:165], v[174:175]
	v_pk_add_f32 v[174:175], v[176:177], v[190:191]
	v_pk_add_f32 v[176:177], v[192:193], v[202:203]
	v_pk_add_f32 v[186:187], v[204:205], v[206:207]
	v_lshlrev_b32_e32 v147, 2, v147
	v_mov_b32_e32 v162, v174
	v_mov_b32_e32 v163, v164
	v_mov_b32_e32 v164, v175
	v_mov_b32_e32 v174, v186
	v_mov_b32_e32 v175, v176
	v_mov_b32_e32 v176, v187
	s_waitcnt lgkmcnt(0)
	v_pk_add_f32 v[152:153], v[152:153], v[188:189]
	v_pk_add_f32 v[162:163], v[162:163], v[164:165]
	v_pk_add_f32 v[164:165], v[174:175], v[176:177]
	ds_bpermute_b32 v175, v147, v153
	ds_bpermute_b32 v174, v147, v152
	ds_bpermute_b32 v177, v151, v163
	ds_bpermute_b32 v176, v151, v162
	v_mov_b32_e32 v208, v215
	v_mov_b32_e32 v209, v216
	s_waitcnt lgkmcnt(2)
	v_pk_add_f32 v[152:153], v[152:153], v[174:175]
	v_mov_b32_e32 v215, v217
	v_pk_fma_f32 v[190:191], v[152:153], s[26:27], v[142:143] op_sel_hi:[1,0,0]
	v_pk_add_f32 v[202:203], v[208:209], v[214:215]
	v_mul_f32_e32 v152, 0x4b800000, v191
	v_cmp_gt_f32_e32 vcc, s19, v191
	s_waitcnt lgkmcnt(0)
	v_pk_add_f32 v[186:187], v[162:163], v[176:177]
	v_mov_b32_e32 v163, v202
	v_cndmask_b32_e32 v152, v191, v152, vcc
	v_rsq_f32_e32 v152, v152
	ds_bpermute_b32 v205, v151, v165
	ds_bpermute_b32 v204, v151, v164
	ds_bpermute_b32 v189, v147, v187
	v_mul_f32_e32 v153, 0x45800000, v152
	v_cndmask_b32_e32 v192, v152, v153, vcc
	v_mov_b32_e32 v152, v219
	v_mov_b32_e32 v153, v220
	v_mov_b32_e32 v219, v221
	v_pk_add_f32 v[152:153], v[152:153], v[218:219]
	s_waitcnt lgkmcnt(1)
	v_pk_add_f32 v[174:175], v[164:165], v[204:205]
	v_mov_b32_e32 v162, v152
	v_mov_b32_e32 v202, v153
	v_pk_add_f32 v[152:153], v[162:163], v[202:203]
	ds_bpermute_b32 v163, v151, v153
	ds_bpermute_b32 v162, v151, v152
	ds_bpermute_b32 v188, v147, v186
	ds_bpermute_b32 v177, v147, v175
	ds_bpermute_b32 v176, v147, v174
	v_cmp_gt_f32_e64 s[10:11], s19, v190
	s_waitcnt lgkmcnt(3)
	v_pk_add_f32 v[162:163], v[152:153], v[162:163]
	ds_bpermute_b32 v165, v147, v163
	ds_bpermute_b32 v164, v147, v162
	v_lshl_or_b32 v152, s0, 8, v194
	v_pk_mul_f32 v[126:127], v[126:127], v[192:193] op_sel_hi:[1,0]
	v_pk_mul_f32 v[124:125], v[124:125], v[192:193] op_sel_hi:[1,0]
	v_pk_mul_f32 v[122:123], v[122:123], v[192:193] op_sel_hi:[1,0]
	v_pk_mul_f32 v[120:121], v[120:121], v[192:193] op_sel_hi:[1,0]
	v_cmp_gt_i32_e32 vcc, s67, v152
	v_ashrrev_i32_e32 v153, 31, v152
	s_and_saveexec_b64 s[8:9], vcc
	s_cbranch_execz .LBB0_812
	v_mov_b64_e32 v[206:207], s[98:99]
	v_mad_i64_i32 v[206:207], s[16:17], v184, s68, v[206:207]
	v_cvt_pk_bf16_f32 v205, v122, v123
	v_cvt_pk_bf16_f32 v204, v120, v121
	v_cvt_pk_bf16_f32 v203, v126, v127
	v_cvt_pk_bf16_f32 v202, v124, v125
	v_lshl_add_u64 v[206:207], v[152:153], 1, v[206:207]
	global_store_dwordx4 v[206:207], v[202:205], off
.LBB0_812:
	s_or_b64 exec, exec, s[8:9]
	v_mov_b32_e32 v193, v192
	v_or_b32_e32 v157, 0x80, v152
	v_mov_b32_e32 v202, v192
	v_mov_b32_e32 v203, v192
	v_pk_mul_f32 v[118:119], v[118:119], v[202:203]
	v_pk_mul_f32 v[116:117], v[116:117], v[192:193]
	v_pk_mul_f32 v[114:115], v[114:115], v[202:203]
	v_pk_mul_f32 v[112:113], v[112:113], v[192:193]
	v_cmp_gt_i32_e64 s[8:9], s67, v157
	s_and_saveexec_b64 s[40:41], s[8:9]
	s_cbranch_execz .LBB0_814
	v_mov_b64_e32 v[192:193], s[98:99]
	v_mad_i64_i32 v[184:185], s[16:17], v184, s68, v[192:193]
	v_cvt_pk_bf16_f32 v205, v114, v115
	v_cvt_pk_bf16_f32 v204, v112, v113
	v_cvt_pk_bf16_f32 v203, v118, v119
	v_cvt_pk_bf16_f32 v202, v116, v117
	v_lshl_add_u64 v[184:185], v[152:153], 1, v[184:185]
	global_store_dwordx4 v[184:185], v[202:205], off offset:256

; DI unsigned pack2(float a, float b) { bf2_t v = __builtin_convertvector((f32x2){a, b}, bf2_t); return __builtin_bit_cast(unsigned, v); }
;   DI void operator()(const f32x4 (&acc)[2][2][4][2], const Unit& u, int wr, int wc, int fr, int fq) const {
;     ...
; #pragma unroll
;     for (int ai = 0; ai < 2; ++ai)
; #pragma unroll
;       for (int m = 0; m < 4; ++m) {
;         const int row = u.pm * BM + ai * HALF + wr * 64 + m * 16 + fr;
;         const float rs = ps_in ? rsv[ai][m] : 1.f;
;         float ssum = 0.f;
; #pragma unroll
;         for (int bj = 0; bj < 2; ++bj) {
;           const int c0 = u.pn * BM + bj * HALF + wc * 32 + 8 * fq;
;           const f32x4 v0 = acc[ai][bj][m][0] * rs, v1 = acc[ai][bj][m][1] * rs;
;           if (PSOUT) ssum += (v0[0] * v0[0] + v0[1] * v0[1]) + (v0[2] * v0[2] + v0[3] * v0[3]) + (v1[0] * v1[0] + v1[1] * v1[1]) + (v1[2] * v1[2] + v1[3] * v1[3]);
;           u32x4 w; w.x = pack2(v0[0], v0[1]); w.y = pack2(v0[2], v0[3]); w.z = pack2(v1[0], v1[1]); w.w = pack2(v1[2], v1[3]);
;           if (EMODE == EM_KVUP) {
;             const int hh = c0 >> 7, j = c0 & 127;
;             if (j < 64) *(u32x4*)(O + (size_t)row * 1152 + hh * 96 + j) = w; else *(u32x4*)(O2 + (size_t)row * 768 + hh * 64 + (j - 64)) = w;
;           } else {
;             if (c0 < ncols) *(u32x4*)(O + (size_t)row * ldo + c0) = w;
;           }
;         }
.LBB0_816:
	s_or_b64 exec, exec, s[0:1]
	v_mul_f32_e32 v112, 0x4b800000, v190
	v_cndmask_b32_e64 v112, v190, v112, s[10:11]
	v_rsq_f32_e32 v112, v112
	s_waitcnt lgkmcnt(0)
	v_mul_f32_e32 v113, 0x45800000, v112
	v_cndmask_b32_e64 v112, v112, v113, s[10:11]
	v_pk_mul_f32 v[110:111], v[110:111], v[112:113] op_sel_hi:[1,0]
	v_pk_mul_f32 v[108:109], v[108:109], v[112:113] op_sel_hi:[1,0]
	v_pk_mul_f32 v[106:107], v[106:107], v[112:113] op_sel_hi:[1,0]
	v_pk_mul_f32 v[104:105], v[104:105], v[112:113] op_sel_hi:[1,0]
	s_and_saveexec_b64 s[0:1], vcc
	s_cbranch_execz .LBB0_818
	v_mov_b64_e32 v[118:119], s[98:99]
	v_mad_i64_i32 v[118:119], s[10:11], v180, s68, v[118:119]
	v_cvt_pk_bf16_f32 v117, v106, v107
	v_cvt_pk_bf16_f32 v116, v104, v105
	v_cvt_pk_bf16_f32 v115, v110, v111
	v_cvt_pk_bf16_f32 v114, v108, v109
	v_lshl_add_u64 v[118:119], v[152:153], 1, v[118:119]
	global_store_dwordx4 v[118:119], v[114:117], off
.LBB0_818:
	s_or_b64 exec, exec, s[0:1]
	v_mov_b32_e32 v113, v112
	v_mov_b32_e32 v114, v112
	v_mov_b32_e32 v115, v112
	v_pk_mul_f32 v[102:103], v[102:103], v[114:115]
	v_pk_mul_f32 v[100:101], v[100:101], v[112:113]
	v_pk_mul_f32 v[98:99], v[98:99], v[114:115]
	v_pk_mul_f32 v[96:97], v[96:97], v[112:113]
	s_and_saveexec_b64 s[0:1], s[8:9]
	s_cbranch_execz .LBB0_820
	v_mov_b64_e32 v[116:117], s[98:99]
	v_mad_i64_i32 v[116:117], s[10:11], v180, s68, v[116:117]
	v_cvt_pk_bf16_f32 v115, v98, v99
	v_cvt_pk_bf16_f32 v114, v96, v97
	v_cvt_pk_bf16_f32 v113, v102, v103
	v_cvt_pk_bf16_f32 v112, v100, v101
	v_lshl_add_u64 v[116:117], v[152:153], 1, v[116:117]
	global_store_dwordx4 v[116:117], v[112:115], off offset:256

; DI unsigned pack2(float a, float b) { bf2_t v = __builtin_convertvector((f32x2){a, b}, bf2_t); return __builtin_bit_cast(unsigned, v); }
;   DI void operator()(const f32x4 (&acc)[2][2][4][2], const Unit& u, int wr, int wc, int fr, int fq) const {
;     ...
; #pragma unroll
;     for (int ai = 0; ai < 2; ++ai)
; #pragma unroll
;       for (int m = 0; m < 4; ++m) {
;         const int row = u.pm * BM + ai * HALF + wr * 64 + m * 16 + fr;
;         const float rs = ps_in ? rsv[ai][m] : 1.f;
;         float ssum = 0.f;
; #pragma unroll
;         for (int bj = 0; bj < 2; ++bj) {
;           const int c0 = u.pn * BM + bj * HALF + wc * 32 + 8 * fq;
;           const f32x4 v0 = acc[ai][bj][m][0] * rs, v1 = acc[ai][bj][m][1] * rs;
;           if (PSOUT) ssum += (v0[0] * v0[0] + v0[1] * v0[1]) + (v0[2] * v0[2] + v0[3] * v0[3]) + (v1[0] * v1[0] + v1[1] * v1[1]) + (v1[2] * v1[2] + v1[3] * v1[3]);
;           u32x4 w; w.x = pack2(v0[0], v0[1]); w.y = pack2(v0[2], v0[3]); w.z = pack2(v1[0], v1[1]); w.w = pack2(v1[2], v1[3]);
;           if (EMODE == EM_KVUP) {
;             const int hh = c0 >> 7, j = c0 & 127;
;             if (j < 64) *(u32x4*)(O + (size_t)row * 1152 + hh * 96 + j) = w; else *(u32x4*)(O2 + (size_t)row * 768 + hh * 64 + (j - 64)) = w;
;           } else {
;             if (c0 < ncols) *(u32x4*)(O + (size_t)row * ldo + c0) = w;
;           }
;         }
.LBB0_822:
	s_or_b64 exec, exec, s[0:1]
	s_waitcnt lgkmcnt(0)
	v_pk_add_f32 v[96:97], v[186:187], v[188:189]
	s_nop 0
	v_pk_fma_f32 v[96:97], v[96:97], s[26:27], v[142:143] op_sel_hi:[1,0,0]
	s_nop 0
	v_mul_f32_e32 v98, 0x4b800000, v97
	v_cmp_gt_f32_e64 s[0:1], s19, v97
	v_cmp_gt_f32_e64 s[10:11], s19, v96
	s_nop 0
	v_cndmask_b32_e64 v97, v97, v98, s[0:1]
	v_rsq_f32_e32 v97, v97
	s_nop 0
	v_mul_f32_e32 v98, 0x45800000, v97
	v_cndmask_b32_e64 v98, v97, v98, s[0:1]
	v_pk_mul_f32 v[94:95], v[94:95], v[98:99] op_sel_hi:[1,0]
	v_pk_mul_f32 v[92:93], v[92:93], v[98:99] op_sel_hi:[1,0]
	v_pk_mul_f32 v[90:91], v[90:91], v[98:99] op_sel_hi:[1,0]
	v_pk_mul_f32 v[88:89], v[88:89], v[98:99] op_sel_hi:[1,0]
	s_and_saveexec_b64 s[0:1], vcc
	s_cbranch_execz .LBB0_824
	v_mov_b64_e32 v[104:105], s[98:99]
	v_mad_i64_i32 v[104:105], s[16:17], v172, s68, v[104:105]
	v_cvt_pk_bf16_f32 v103, v90, v91
	v_cvt_pk_bf16_f32 v102, v88, v89
	v_cvt_pk_bf16_f32 v101, v94, v95
	v_cvt_pk_bf16_f32 v100, v92, v93
	v_lshl_add_u64 v[104:105], v[152:153], 1, v[104:105]
	global_store_dwordx4 v[104:105], v[100:103], off
.LBB0_824:
	s_or_b64 exec, exec, s[0:1]
	v_mov_b32_e32 v99, v98
	v_mov_b32_e32 v100, v98
	v_mov_b32_e32 v101, v98
	v_pk_mul_f32 v[86:87], v[86:87], v[100:101]
	v_pk_mul_f32 v[84:85], v[84:85], v[98:99]
	v_pk_mul_f32 v[82:83], v[82:83], v[100:101]
	v_pk_mul_f32 v[80:81], v[80:81], v[98:99]
	s_and_saveexec_b64 s[0:1], s[8:9]
	s_cbranch_execz .LBB0_826
	v_mov_b64_e32 v[102:103], s[98:99]
	v_mad_i64_i32 v[102:103], s[16:17], v172, s68, v[102:103]
	v_cvt_pk_bf16_f32 v101, v82, v83
	v_cvt_pk_bf16_f32 v100, v80, v81
	v_cvt_pk_bf16_f32 v99, v86, v87
	v_cvt_pk_bf16_f32 v98, v84, v85
	v_lshl_add_u64 v[102:103], v[152:153], 1, v[102:103]
	global_store_dwordx4 v[102:103], v[98:101], off offset:256

; DI unsigned pack2(float a, float b) { bf2_t v = __builtin_convertvector((f32x2){a, b}, bf2_t); return __builtin_bit_cast(unsigned, v); }
;   DI void operator()(const f32x4 (&acc)[2][2][4][2], const Unit& u, int wr, int wc, int fr, int fq) const {
;     ...
; #pragma unroll
;     for (int ai = 0; ai < 2; ++ai)
; #pragma unroll
;       for (int m = 0; m < 4; ++m) {
;         const int row = u.pm * BM + ai * HALF + wr * 64 + m * 16 + fr;
;         const float rs = ps_in ? rsv[ai][m] : 1.f;
;         float ssum = 0.f;
; #pragma unroll
;         for (int bj = 0; bj < 2; ++bj) {
;           const int c0 = u.pn * BM + bj * HALF + wc * 32 + 8 * fq;
;           const f32x4 v0 = acc[ai][bj][m][0] * rs, v1 = acc[ai][bj][m][1] * rs;
;           if (PSOUT) ssum += (v0[0] * v0[0] + v0[1] * v0[1]) + (v0[2] * v0[2] + v0[3] * v0[3]) + (v1[0] * v1[0] + v1[1] * v1[1]) + (v1[2] * v1[2] + v1[3] * v1[3]);
;           u32x4 w; w.x = pack2(v0[0], v0[1]); w.y = pack2(v0[2], v0[3]); w.z = pack2(v1[0], v1[1]); w.w = pack2(v1[2], v1[3]);
;           if (EMODE == EM_KVUP) {
;             const int hh = c0 >> 7, j = c0 & 127;
;             if (j < 64) *(u32x4*)(O + (size_t)row * 1152 + hh * 96 + j) = w; else *(u32x4*)(O2 + (size_t)row * 768 + hh * 64 + (j - 64)) = w;
;           } else {
;             if (c0 < ncols) *(u32x4*)(O + (size_t)row * ldo + c0) = w;
;           }
;         }
.LBB0_828:
	s_or_b64 exec, exec, s[0:1]
	v_mul_f32_e32 v80, 0x4b800000, v96
	v_cndmask_b32_e64 v80, v96, v80, s[10:11]
	v_rsq_f32_e32 v80, v80
	s_waitcnt lgkmcnt(0)
	v_mul_f32_e32 v81, 0x45800000, v80
	v_cndmask_b32_e64 v80, v80, v81, s[10:11]
	v_pk_mul_f32 v[78:79], v[78:79], v[80:81] op_sel_hi:[1,0]
	v_pk_mul_f32 v[76:77], v[76:77], v[80:81] op_sel_hi:[1,0]
	v_pk_mul_f32 v[74:75], v[74:75], v[80:81] op_sel_hi:[1,0]
	v_pk_mul_f32 v[72:73], v[72:73], v[80:81] op_sel_hi:[1,0]
	s_and_saveexec_b64 s[0:1], vcc
	s_cbranch_execz .LBB0_830
	v_mov_b64_e32 v[86:87], s[98:99]
	v_mad_i64_i32 v[86:87], s[10:11], v168, s68, v[86:87]
	v_cvt_pk_bf16_f32 v85, v74, v75
	v_cvt_pk_bf16_f32 v84, v72, v73
	v_cvt_pk_bf16_f32 v83, v78, v79
	v_cvt_pk_bf16_f32 v82, v76, v77
	v_lshl_add_u64 v[86:87], v[152:153], 1, v[86:87]
	global_store_dwordx4 v[86:87], v[82:85], off
.LBB0_830:
	s_or_b64 exec, exec, s[0:1]
	v_mov_b32_e32 v81, v80
	v_mov_b32_e32 v82, v80
	v_mov_b32_e32 v83, v80
	v_pk_mul_f32 v[70:71], v[70:71], v[82:83]
	v_pk_mul_f32 v[68:69], v[68:69], v[80:81]
	v_pk_mul_f32 v[66:67], v[66:67], v[82:83]
	v_pk_mul_f32 v[64:65], v[64:65], v[80:81]
	s_and_saveexec_b64 s[0:1], s[8:9]
	s_cbranch_execz .LBB0_832
	v_mov_b64_e32 v[84:85], s[98:99]
	v_mad_i64_i32 v[84:85], s[10:11], v168, s68, v[84:85]
	v_cvt_pk_bf16_f32 v83, v66, v67
	v_cvt_pk_bf16_f32 v82, v64, v65
	v_cvt_pk_bf16_f32 v81, v70, v71
	v_cvt_pk_bf16_f32 v80, v68, v69
	v_lshl_add_u64 v[84:85], v[152:153], 1, v[84:85]
	global_store_dwordx4 v[84:85], v[80:83], off offset:256

; DI unsigned pack2(float a, float b) { bf2_t v = __builtin_convertvector((f32x2){a, b}, bf2_t); return __builtin_bit_cast(unsigned, v); }
;   DI void operator()(const f32x4 (&acc)[2][2][4][2], const Unit& u, int wr, int wc, int fr, int fq) const {
;     ...
; #pragma unroll
;     for (int ai = 0; ai < 2; ++ai)
; #pragma unroll
;       for (int m = 0; m < 4; ++m) {
;         const int row = u.pm * BM + ai * HALF + wr * 64 + m * 16 + fr;
;         const float rs = ps_in ? rsv[ai][m] : 1.f;
;         float ssum = 0.f;
; #pragma unroll
;         for (int bj = 0; bj < 2; ++bj) {
;           const int c0 = u.pn * BM + bj * HALF + wc * 32 + 8 * fq;
;           const f32x4 v0 = acc[ai][bj][m][0] * rs, v1 = acc[ai][bj][m][1] * rs;
;           if (PSOUT) ssum += (v0[0] * v0[0] + v0[1] * v0[1]) + (v0[2] * v0[2] + v0[3] * v0[3]) + (v1[0] * v1[0] + v1[1] * v1[1]) + (v1[2] * v1[2] + v1[3] * v1[3]);
;           u32x4 w; w.x = pack2(v0[0], v0[1]); w.y = pack2(v0[2], v0[3]); w.z = pack2(v1[0], v1[1]); w.w = pack2(v1[2], v1[3]);
;           if (EMODE == EM_KVUP) {
;             const int hh = c0 >> 7, j = c0 & 127;
;             if (j < 64) *(u32x4*)(O + (size_t)row * 1152 + hh * 96 + j) = w; else *(u32x4*)(O2 + (size_t)row * 768 + hh * 64 + (j - 64)) = w;
;           } else {
;             if (c0 < ncols) *(u32x4*)(O + (size_t)row * ldo + c0) = w;
;           }
;         }
.LBB0_834:
	s_or_b64 exec, exec, s[0:1]
	s_waitcnt lgkmcnt(0)
	v_pk_add_f32 v[64:65], v[174:175], v[176:177]
	s_nop 0
	v_pk_fma_f32 v[64:65], v[64:65], s[26:27], v[142:143] op_sel_hi:[1,0,0]
	s_nop 0
	v_mul_f32_e32 v66, 0x4b800000, v65
	v_cmp_gt_f32_e64 s[0:1], s19, v65
	v_cmp_gt_f32_e64 s[10:11], s19, v64
	s_nop 0
	v_cndmask_b32_e64 v65, v65, v66, s[0:1]
	v_rsq_f32_e32 v65, v65
	s_nop 0
	v_mul_f32_e32 v66, 0x45800000, v65
	v_cndmask_b32_e64 v66, v65, v66, s[0:1]
	v_pk_mul_f32 v[62:63], v[62:63], v[66:67] op_sel_hi:[1,0]
	v_pk_mul_f32 v[60:61], v[60:61], v[66:67] op_sel_hi:[1,0]
	v_pk_mul_f32 v[58:59], v[58:59], v[66:67] op_sel_hi:[1,0]
	v_pk_mul_f32 v[56:57], v[56:57], v[66:67] op_sel_hi:[1,0]
	s_and_saveexec_b64 s[0:1], vcc
	s_cbranch_execz .LBB0_836
	v_mov_b64_e32 v[72:73], s[98:99]
	v_mad_i64_i32 v[72:73], s[16:17], v160, s68, v[72:73]
	v_cvt_pk_bf16_f32 v71, v58, v59
	v_cvt_pk_bf16_f32 v70, v56, v57
	v_cvt_pk_bf16_f32 v69, v62, v63
	v_cvt_pk_bf16_f32 v68, v60, v61
	v_lshl_add_u64 v[72:73], v[152:153], 1, v[72:73]
	global_store_dwordx4 v[72:73], v[68:71], off
.LBB0_836:
	s_or_b64 exec, exec, s[0:1]
	v_mov_b32_e32 v67, v66
	v_mov_b32_e32 v68, v66
	v_mov_b32_e32 v69, v66
	v_pk_mul_f32 v[54:55], v[54:55], v[68:69]
	v_pk_mul_f32 v[52:53], v[52:53], v[66:67]
	v_pk_mul_f32 v[50:51], v[50:51], v[68:69]
	v_pk_mul_f32 v[48:49], v[48:49], v[66:67]
	s_and_saveexec_b64 s[0:1], s[8:9]
	s_cbranch_execz .LBB0_838
	v_mov_b64_e32 v[70:71], s[98:99]
	v_mad_i64_i32 v[70:71], s[16:17], v160, s68, v[70:71]
	v_cvt_pk_bf16_f32 v69, v50, v51
	v_cvt_pk_bf16_f32 v68, v48, v49
	v_cvt_pk_bf16_f32 v67, v54, v55
	v_cvt_pk_bf16_f32 v66, v52, v53
	v_lshl_add_u64 v[70:71], v[152:153], 1, v[70:71]
	global_store_dwordx4 v[70:71], v[66:69], off offset:256

; DI unsigned pack2(float a, float b) { bf2_t v = __builtin_convertvector((f32x2){a, b}, bf2_t); return __builtin_bit_cast(unsigned, v); }
;   DI void operator()(const f32x4 (&acc)[2][2][4][2], const Unit& u, int wr, int wc, int fr, int fq) const {
;     ...
; #pragma unroll
;     for (int ai = 0; ai < 2; ++ai)
; #pragma unroll
;       for (int m = 0; m < 4; ++m) {
;         const int row = u.pm * BM + ai * HALF + wr * 64 + m * 16 + fr;
;         const float rs = ps_in ? rsv[ai][m] : 1.f;
;         float ssum = 0.f;
; #pragma unroll
;         for (int bj = 0; bj < 2; ++bj) {
;           const int c0 = u.pn * BM + bj * HALF + wc * 32 + 8 * fq;
;           const f32x4 v0 = acc[ai][bj][m][0] * rs, v1 = acc[ai][bj][m][1] * rs;
;           if (PSOUT) ssum += (v0[0] * v0[0] + v0[1] * v0[1]) + (v0[2] * v0[2] + v0[3] * v0[3]) + (v1[0] * v1[0] + v1[1] * v1[1]) + (v1[2] * v1[2] + v1[3] * v1[3]);
;           u32x4 w; w.x = pack2(v0[0], v0[1]); w.y = pack2(v0[2], v0[3]); w.z = pack2(v1[0], v1[1]); w.w = pack2(v1[2], v1[3]);
;           if (EMODE == EM_KVUP) {
;             const int hh = c0 >> 7, j = c0 & 127;
;             if (j < 64) *(u32x4*)(O + (size_t)row * 1152 + hh * 96 + j) = w; else *(u32x4*)(O2 + (size_t)row * 768 + hh * 64 + (j - 64)) = w;
;           } else {
;             if (c0 < ncols) *(u32x4*)(O + (size_t)row * ldo + c0) = w;
;           }
;         }
.LBB0_840:
	s_or_b64 exec, exec, s[0:1]
	v_mul_f32_e32 v48, 0x4b800000, v64
	v_cndmask_b32_e64 v48, v64, v48, s[10:11]
	v_rsq_f32_e32 v48, v48
	s_waitcnt lgkmcnt(0)
	v_mul_f32_e32 v49, 0x45800000, v48
	v_cndmask_b32_e64 v48, v48, v49, s[10:11]
	v_pk_mul_f32 v[46:47], v[46:47], v[48:49] op_sel_hi:[1,0]
	v_pk_mul_f32 v[44:45], v[44:45], v[48:49] op_sel_hi:[1,0]
	v_pk_mul_f32 v[42:43], v[42:43], v[48:49] op_sel_hi:[1,0]
	v_pk_mul_f32 v[40:41], v[40:41], v[48:49] op_sel_hi:[1,0]
	s_and_saveexec_b64 s[0:1], vcc
	s_cbranch_execz .LBB0_842
	v_mov_b64_e32 v[54:55], s[98:99]
	v_mad_i64_i32 v[54:55], s[10:11], v156, s68, v[54:55]
	v_cvt_pk_bf16_f32 v53, v42, v43
	v_cvt_pk_bf16_f32 v52, v40, v41
	v_cvt_pk_bf16_f32 v51, v46, v47
	v_cvt_pk_bf16_f32 v50, v44, v45
	v_lshl_add_u64 v[54:55], v[152:153], 1, v[54:55]
	global_store_dwordx4 v[54:55], v[50:53], off
.LBB0_842:
	s_or_b64 exec, exec, s[0:1]
	v_mov_b32_e32 v49, v48
	v_mov_b32_e32 v50, v48
	v_mov_b32_e32 v51, v48
	v_pk_mul_f32 v[38:39], v[38:39], v[50:51]
	v_pk_mul_f32 v[36:37], v[36:37], v[48:49]
	v_pk_mul_f32 v[34:35], v[34:35], v[50:51]
	v_pk_mul_f32 v[32:33], v[32:33], v[48:49]
	s_and_saveexec_b64 s[0:1], s[8:9]
	s_cbranch_execz .LBB0_844
	v_mov_b64_e32 v[52:53], s[98:99]
	v_mad_i64_i32 v[52:53], s[10:11], v156, s68, v[52:53]
	v_cvt_pk_bf16_f32 v51, v34, v35
	v_cvt_pk_bf16_f32 v50, v32, v33
	v_cvt_pk_bf16_f32 v49, v38, v39
	v_cvt_pk_bf16_f32 v48, v36, v37
	v_lshl_add_u64 v[52:53], v[152:153], 1, v[52:53]
	global_store_dwordx4 v[52:53], v[48:51], off offset:256

; DI unsigned pack2(float a, float b) { bf2_t v = __builtin_convertvector((f32x2){a, b}, bf2_t); return __builtin_bit_cast(unsigned, v); }
;   DI void operator()(const f32x4 (&acc)[2][2][4][2], const Unit& u, int wr, int wc, int fr, int fq) const {
;     ...
; #pragma unroll
;     for (int ai = 0; ai < 2; ++ai)
; #pragma unroll
;       for (int m = 0; m < 4; ++m) {
;         const int row = u.pm * BM + ai * HALF + wr * 64 + m * 16 + fr;
;         const float rs = ps_in ? rsv[ai][m] : 1.f;
;         float ssum = 0.f;
; #pragma unroll
;         for (int bj = 0; bj < 2; ++bj) {
;           const int c0 = u.pn * BM + bj * HALF + wc * 32 + 8 * fq;
;           const f32x4 v0 = acc[ai][bj][m][0] * rs, v1 = acc[ai][bj][m][1] * rs;
;           if (PSOUT) ssum += (v0[0] * v0[0] + v0[1] * v0[1]) + (v0[2] * v0[2] + v0[3] * v0[3]) + (v1[0] * v1[0] + v1[1] * v1[1]) + (v1[2] * v1[2] + v1[3] * v1[3]);
;           u32x4 w; w.x = pack2(v0[0], v0[1]); w.y = pack2(v0[2], v0[3]); w.z = pack2(v1[0], v1[1]); w.w = pack2(v1[2], v1[3]);
;           if (EMODE == EM_KVUP) {
;             const int hh = c0 >> 7, j = c0 & 127;
;             if (j < 64) *(u32x4*)(O + (size_t)row * 1152 + hh * 96 + j) = w; else *(u32x4*)(O2 + (size_t)row * 768 + hh * 64 + (j - 64)) = w;
;           } else {
;             if (c0 < ncols) *(u32x4*)(O + (size_t)row * ldo + c0) = w;
;           }
;         }
.LBB0_846:
	s_or_b64 exec, exec, s[0:1]
	s_waitcnt lgkmcnt(0)
	v_pk_add_f32 v[32:33], v[162:163], v[164:165]
	s_nop 0
	v_pk_fma_f32 v[32:33], v[32:33], s[26:27], v[142:143] op_sel_hi:[1,0,0]
	s_nop 0
	v_mul_f32_e32 v34, 0x4b800000, v33
	v_cmp_gt_f32_e64 s[0:1], s19, v33
	v_cmp_gt_f32_e64 s[10:11], s19, v32
	s_nop 0
	v_cndmask_b32_e64 v33, v33, v34, s[0:1]
	v_rsq_f32_e32 v33, v33
	s_nop 0
	v_mul_f32_e32 v34, 0x45800000, v33
	v_cndmask_b32_e64 v34, v33, v34, s[0:1]
	v_pk_mul_f32 v[30:31], v[30:31], v[34:35] op_sel_hi:[1,0]
	v_pk_mul_f32 v[28:29], v[28:29], v[34:35] op_sel_hi:[1,0]
	v_pk_mul_f32 v[26:27], v[26:27], v[34:35] op_sel_hi:[1,0]
	v_pk_mul_f32 v[24:25], v[24:25], v[34:35] op_sel_hi:[1,0]
	s_and_saveexec_b64 s[0:1], vcc
	s_cbranch_execz .LBB0_848
	v_mov_b64_e32 v[40:41], s[98:99]
	v_mad_i64_i32 v[40:41], s[16:17], v150, s68, v[40:41]
	v_cvt_pk_bf16_f32 v39, v26, v27
	v_cvt_pk_bf16_f32 v38, v24, v25
	v_cvt_pk_bf16_f32 v37, v30, v31
	v_cvt_pk_bf16_f32 v36, v28, v29
	v_lshl_add_u64 v[40:41], v[152:153], 1, v[40:41]
	global_store_dwordx4 v[40:41], v[36:39], off
.LBB0_848:
	s_or_b64 exec, exec, s[0:1]
	v_mov_b32_e32 v35, v34
	v_mov_b32_e32 v36, v34
	v_mov_b32_e32 v37, v34
	v_pk_mul_f32 v[22:23], v[22:23], v[36:37]
	v_pk_mul_f32 v[20:21], v[20:21], v[34:35]
	v_pk_mul_f32 v[18:19], v[18:19], v[36:37]
	v_pk_mul_f32 v[16:17], v[16:17], v[34:35]
	s_and_saveexec_b64 s[0:1], s[8:9]
	s_cbranch_execz .LBB0_850
	v_mov_b64_e32 v[38:39], s[98:99]
	v_mad_i64_i32 v[38:39], s[16:17], v150, s68, v[38:39]
	v_cvt_pk_bf16_f32 v37, v18, v19
	v_cvt_pk_bf16_f32 v36, v16, v17
	v_cvt_pk_bf16_f32 v35, v22, v23
	v_cvt_pk_bf16_f32 v34, v20, v21
	v_lshl_add_u64 v[38:39], v[152:153], 1, v[38:39]
	global_store_dwordx4 v[38:39], v[34:37], off offset:256

; DI unsigned pack2(float a, float b) { bf2_t v = __builtin_convertvector((f32x2){a, b}, bf2_t); return __builtin_bit_cast(unsigned, v); }
;   DI void operator()(const f32x4 (&acc)[2][2][4][2], const Unit& u, int wr, int wc, int fr, int fq) const {
;     ...
; #pragma unroll
;     for (int ai = 0; ai < 2; ++ai)
; #pragma unroll
;       for (int m = 0; m < 4; ++m) {
;         const int row = u.pm * BM + ai * HALF + wr * 64 + m * 16 + fr;
;         const float rs = ps_in ? rsv[ai][m] : 1.f;
;         float ssum = 0.f;
; #pragma unroll
;         for (int bj = 0; bj < 2; ++bj) {
;           const int c0 = u.pn * BM + bj * HALF + wc * 32 + 8 * fq;
;           const f32x4 v0 = acc[ai][bj][m][0] * rs, v1 = acc[ai][bj][m][1] * rs;
;           if (PSOUT) ssum += (v0[0] * v0[0] + v0[1] * v0[1]) + (v0[2] * v0[2] + v0[3] * v0[3]) + (v1[0] * v1[0] + v1[1] * v1[1]) + (v1[2] * v1[2] + v1[3] * v1[3]);
;           u32x4 w; w.x = pack2(v0[0], v0[1]); w.y = pack2(v0[2], v0[3]); w.z = pack2(v1[0], v1[1]); w.w = pack2(v1[2], v1[3]);
;           if (EMODE == EM_KVUP) {
;             const int hh = c0 >> 7, j = c0 & 127;
;             if (j < 64) *(u32x4*)(O + (size_t)row * 1152 + hh * 96 + j) = w; else *(u32x4*)(O2 + (size_t)row * 768 + hh * 64 + (j - 64)) = w;
;           } else {
;             if (c0 < ncols) *(u32x4*)(O + (size_t)row * ldo + c0) = w;
;           }
;         }
.LBB0_852:
	s_or_b64 exec, exec, s[0:1]
	v_mul_f32_e32 v16, 0x4b800000, v32
	v_cndmask_b32_e64 v16, v32, v16, s[10:11]
	v_rsq_f32_e32 v16, v16
	s_waitcnt lgkmcnt(0)
	v_mul_f32_e32 v17, 0x45800000, v16
	v_cndmask_b32_e64 v16, v16, v17, s[10:11]
	v_pk_mul_f32 v[14:15], v[14:15], v[16:17] op_sel_hi:[1,0]
	v_pk_mul_f32 v[12:13], v[12:13], v[16:17] op_sel_hi:[1,0]
	v_pk_mul_f32 v[10:11], v[10:11], v[16:17] op_sel_hi:[1,0]
	v_pk_mul_f32 v[8:9], v[8:9], v[16:17] op_sel_hi:[1,0]
	s_and_saveexec_b64 s[0:1], vcc
	s_cbranch_execz .LBB0_854
	v_mov_b64_e32 v[22:23], s[98:99]
	v_mad_i64_i32 v[22:23], s[10:11], v146, s68, v[22:23]
	v_cvt_pk_bf16_f32 v21, v10, v11
	v_cvt_pk_bf16_f32 v20, v8, v9
	v_cvt_pk_bf16_f32 v19, v14, v15
	v_cvt_pk_bf16_f32 v18, v12, v13
	v_lshl_add_u64 v[22:23], v[152:153], 1, v[22:23]
	global_store_dwordx4 v[22:23], v[18:21], off
.LBB0_854:
	s_or_b64 exec, exec, s[0:1]
	v_mov_b32_e32 v17, v16
	v_mov_b32_e32 v18, v16
	v_mov_b32_e32 v19, v16
	v_pk_mul_f32 v[6:7], v[6:7], v[18:19]
	v_pk_mul_f32 v[4:5], v[4:5], v[16:17]
	v_pk_mul_f32 v[2:3], v[2:3], v[18:19]
	v_pk_mul_f32 v[0:1], v[0:1], v[16:17]
	s_and_saveexec_b64 s[0:1], s[8:9]
	s_cbranch_execz .LBB0_856
	v_mov_b64_e32 v[20:21], s[98:99]
	v_mad_i64_i32 v[20:21], s[8:9], v146, s68, v[20:21]
	v_cvt_pk_bf16_f32 v19, v2, v3
	v_cvt_pk_bf16_f32 v18, v0, v1
	v_cvt_pk_bf16_f32 v17, v6, v7
	v_cvt_pk_bf16_f32 v16, v4, v5
	v_lshl_add_u64 v[20:21], v[152:153], 1, v[20:21]
	global_store_dwordx4 v[20:21], v[16:19], off offset:256

; DI unsigned xb_ld(unsigned* p) { return __hip_atomic_load(p, __ATOMIC_RELAXED, __HIP_MEMORY_SCOPE_AGENT); }
; DI unsigned xb_add(unsigned* p, unsigned v) { return __hip_atomic_fetch_add(p, v, __ATOMIC_RELAXED, __HIP_MEMORY_SCOPE_AGENT); }
; #define XB_SPIN(cond, bar) do { unsigned _sp = 0; while (cond) { __builtin_amdgcn_s_sleep(1); \
;     if ((++_sp & 255u) == 0u) { if (xb_ld(&(bar)[XB_TMO])) break; if (_sp > XB_SPIN_CAP) { atomicAdd(&(bar)[XB_TMO], 1u); break; } } } } while (0)
; DI void xcd_barrier(const XcdBarrier& b) {
;     ...
;       else XB_SPIN(xb_ld(&bar[XB_TOPGEN]) == tg, bar);
;       __builtin_amdgcn_fence(__ATOMIC_ACQUIRE, "agent");
;       xb_add(&bar[XB_XGEN(b.x)], 1u);
;       asm volatile("s_waitcnt vmcnt(0)" ::: "memory");
;     } else {
;       XB_SPIN(xb_ld(&bar[XB_XGEN(b.x)]) == gen, bar);
.Lxl_spin_7:
	v_mov_b32_e32 v255, 0xbfa0210
	global_load_dword v255, v255, s[86:87] sc1
	s_waitcnt vmcnt(0) lgkmcnt(0)
	v_cmp_lt_u32_e32 vcc, v255, v0
	s_cbranch_vccz .Lxl_go_7
	s_sleep 1
	s_branch .Lxl_spin_7

; DI unsigned xb_ld(unsigned* p) { return __hip_atomic_load(p, __ATOMIC_RELAXED, __HIP_MEMORY_SCOPE_AGENT); }
; DI unsigned xb_add(unsigned* p, unsigned v) { return __hip_atomic_fetch_add(p, v, __ATOMIC_RELAXED, __HIP_MEMORY_SCOPE_AGENT); }
; #define XB_SPIN(cond, bar) do { unsigned _sp = 0; while (cond) { __builtin_amdgcn_s_sleep(1); \
;     if ((++_sp & 255u) == 0u) { if (xb_ld(&(bar)[XB_TMO])) break; if (_sp > XB_SPIN_CAP) { atomicAdd(&(bar)[XB_TMO], 1u); break; } } } } while (0)
; DI void xcd_barrier(const XcdBarrier& b) {
;     ...
;     if (old + 1u == (gen + 1u) * nloc) {
;       __builtin_amdgcn_fence(__ATOMIC_RELEASE, "agent");
;       asm volatile("s_waitcnt vmcnt(0)" ::: "memory");
;       const unsigned og = xb_add(&bar[XB_TOP], 1u);
;       const unsigned tg = og / nx;
;       if (og + 1u == (tg + 1u) * nx) xb_add(&bar[XB_TOPGEN], 1u);
;       else XB_SPIN(xb_ld(&bar[XB_TOPGEN]) == tg, bar);
.Lxl_full_7:
	buffer_wbl2 sc1
	s_waitcnt lgkmcnt(0)
	s_waitcnt vmcnt(0)
	v_mbcnt_lo_u32_b32 v0, s8, 0
	v_mbcnt_hi_u32_b32 v0, s9, v0
	v_cmp_eq_u32_e32 vcc, 0, v0
	s_and_saveexec_b64 s[10:11], vcc
	s_cbranch_execz .LBB0_898
	s_bcnt1_i32_b64 s2, s[8:9]
	v_mov_b32_e32 v2, 0xbfa3000
	v_mov_b32_e32 v3, s2
	global_atomic_add v2, v2, v3, s[86:87] offset:1024 sc0
.LBB0_898:
	s_or_b64 exec, exec, s[10:11]
	v_cvt_f32_u32_e32 v3, v1
	s_waitcnt vmcnt(0)
	v_readfirstlane_b32 s2, v2
	s_add_u32 s10, s86, 0xbfa3500
	s_addc_u32 s11, s87, 0
	v_rcp_iflag_f32_e32 v3, v3
	v_add_u32_e32 v0, s2, v0
	v_add_u32_e32 v4, 1, v0
	s_mov_b64 s[12:13], -1
	v_mul_f32_e32 v2, 0x4f7ffffe, v3
	v_cvt_u32_f32_e32 v2, v2
	v_sub_u32_e32 v3, 0, v1
	v_mul_lo_u32 v3, v3, v2
	v_mul_hi_u32 v3, v2, v3
	v_add_u32_e32 v2, v2, v3
	v_mul_hi_u32 v2, v0, v2
	v_mul_lo_u32 v3, v2, v1
	v_sub_u32_e32 v0, v0, v3
	v_add_u32_e32 v5, 1, v2
	v_cmp_ge_u32_e32 vcc, v0, v1
	v_sub_u32_e32 v3, v0, v1
	s_nop 0
	v_cndmask_b32_e32 v2, v2, v5, vcc
	v_cndmask_b32_e32 v0, v0, v3, vcc
	v_add_u32_e32 v3, 1, v2
	v_cmp_ge_u32_e32 vcc, v0, v1
	s_nop 1
	v_cndmask_b32_e32 v2, v2, v3, vcc
	v_mul_lo_u32 v0, v1, v2
	v_add_u32_e32 v0, v0, v1
	v_cmp_ne_u32_e32 vcc, v4, v0
	v_mov_b64_e32 v[0:1], s[10:11]
	s_and_saveexec_b64 s[8:9], vcc
	s_cbranch_execz .LBB0_910
	v_mov_b32_e32 v0, 0
	global_load_dword v1, v0, s[10:11] sc1
	s_mov_b64 s[20:21], 0
	s_waitcnt vmcnt(0)
	v_cmp_eq_u32_e32 vcc, v1, v2
	s_and_saveexec_b64 s[14:15], vcc
	s_cbranch_execz .LBB0_909
	s_add_u32 s12, s86, 0xbfa0200
	s_addc_u32 s13, s87, 0
	s_mov_b32 s2, 1
	s_branch .LBB0_902

; #define PG8_WAIT_V(n) asm volatile("s_waitcnt vmcnt(" #n ")" ::: "memory")
; #define PG8_BAR __builtin_amdgcn_s_barrier()
; template <class Epi, class Sched>
; DI void gemm_phase(PG8_LAS unsigned char* lds, const Gemm g, const Sched& S, const Epi& E) {
;     ...
;   for (int i = 0; i < 2; ++i) { int R, C; stage_rc(tid * 16 + i * 8192, R, C); const int Rb = Epi::PERM ? ((R & ~31) + perm32(R & 31)) : R;
;     voffA[i] = (unsigned)(R * g.lda + C) * 2u; voffB[i] = (unsigned)(Rb * K + C) * 2u; }
;   const size_t kstep = (size_t)(BK * 2);
;   const size_t hstepA = (size_t)HALF * g.lda * 2, hstepB = (size_t)HALF * K * 2;
;   const size_t tstepA = 2 * hstepA, tstepB = 2 * hstepB;
;   const unsigned ldsw = (unsigned)wid * 1024u;
;   const int aoff = lds_byte(wr * 64 + fr, fq * 8), boff = lds_byte(wc * 32 + fr, fq * 8);
;     ...
;   Unit cur, nxt; int ui = 0;
;   if (!S.next(0, cur)) return;
;   f32x4 acc[2][2][4][2];
; #pragma unroll
;   for (int a = 0; a < 2; ++a)
; #pragma unroll
;     for (int b = 0; b < 2; ++b)
; #pragma unroll
;       for (int m = 0; m < 4; ++m)
; #pragma unroll
;         for (int n = 0; n < 2; ++n) acc[a][b][m][n] = (f32x4){0.f, 0.f, 0.f, 0.f};
;   bf16x8 At[4][2], B0[2][2], B1[2][2];
;   const char* cA = (const char*)g.A + (size_t)cur.pm * tstepA; const char* cB = (const char*)g.Bt + (size_t)cur.pn * tstepB;
;   PG8_STAGE(PG8_SB(0, 0), cB, voffB); PG8_STAGE(PG8_SB(0, 1), cB + hstepB, voffB); PG8_STAGE(PG8_SA(0, 0), cA, voffA); PG8_STAGE(PG8_SA(0, 1), cA + hstepA, voffA);
;   if (wr == 1) PG8_BAR;
;   PG8_WAIT_V(2); PG8_BAR;
;   PG8_STAGE(PG8_SB(1, 0), cB + kstep, voffB); PG8_STAGE(PG8_SA(1, 0), cA + kstep, voffA); PG8_STAGE(PG8_SB(1, 1), cB + hstepB + kstep, voffB);
;   PG8_WAIT_V(6); PG8_BAR;
; __global__ void __launch_bounds__(NTHREADS, 2) fwd_megakernel(Params p) {
;     ...
;     pg8::Gemm g{(const bf16_t*)(ws + O_PM), 1408, (const bf16_t*)(ws + O_QUP), T_TOK, 1280, 768};
;     pg8::XOrder S; S.init(T_TOK, 1280, toff);
;     pg8::EpiNorm<pg8::EM_PLAIN> E{(bf16_t*)(ws + O_QB), 1152, 1152, nullptr, ps2, 0, 12, 1.f / 768.f, nullptr};
;     pg8::gemm_phase(lds, g, S, E);
;     pg8::Gemm g2{(const bf16_t*)(ws + O_PM) + 768, 1408, (const bf16_t*)(ws + O_KVUP), T_TOK, 1536, 256};
;     pg8::XOrder S2; S2.init(T_TOK, 1536, toff);
;     pg8::EpiNorm<pg8::EM_KVUP> E2{(bf16_t*)(ws + O_KN), 1152, 1536, (bf16_t*)(ws + O_V1), ps2, 12, 16, 1.f / 256.f, nullptr};
.LBB0_917:
	s_add_u32 s20, s86, 0xbfa4000
	s_addc_u32 s21, s87, 0
	s_andn2_b64 vcc, exec, s[0:1]
	s_cbranch_vccnz .LBB0_971
	v_ashrrev_i32_e32 v1, 31, v8
	v_lshrrev_b32_e32 v1, 26, v1
	v_add_u32_e32 v1, v8, v1
	v_ashrrev_i32_e32 v9, 6, v1
	v_bfe_i32 v1, v8, 27, 1
	v_lshlrev_b32_e32 v0, 4, v8
	v_lshrrev_b32_e32 v1, 22, v1
	v_add_u32_e32 v1, v0, v1
	v_and_b32_e32 v1, 0xfffffc00, v1
	v_sub_u32_e32 v1, v0, v1
	v_lshrrev_b32_e32 v2, 4, v1
	v_bitop3_b32 v2, v2, v1, 32 bitop3:0x6c
	v_ashrrev_i32_e32 v1, 31, v1
	v_lshrrev_b32_e32 v1, 26, v1
	v_lshlrev_b32_e32 v3, 3, v9
	v_add_u32_e32 v1, v2, v1
	v_and_b32_e32 v3, -16, v3
	v_ashrrev_i32_e32 v11, 6, v1
	v_add_u32_e32 v1, v11, v3
	v_lshlrev_b32_e32 v3, 5, v9
	v_and_b32_e32 v10, 32, v3
	v_mul_i32_i24_e32 v3, 64, v11
	v_sub_u32_e32 v2, v2, v3
	v_mov_b32_e32 v3, 1
	v_ashrrev_i16_sdwa v2, v3, sext(v2) dst_sel:DWORD dst_unused:UNUSED_PAD src0_sel:DWORD src1_sel:BYTE_0
	v_lshlrev_b32_e32 v4, 1, v1
	v_lshrrev_b32_e32 v5, 2, v1
	v_and_b32_e32 v6, 3, v11
	s_mov_b32 s0, 0xffffe0
	v_bfe_i32 v12, v2, 0, 16
	v_and_b32_e32 v4, 24, v4
	v_and_b32_e32 v5, 4, v5
	v_and_or_b32 v6, v1, s0, v6
	s_movk_i32 s10, 0x580
	v_add_u32_e32 v2, v10, v12
	v_or3_b32 v4, v6, v5, v4
	v_mul_lo_u32 v1, v1, s10
	v_add_lshl_u32 v156, v2, v1, 1
	v_mul_u32_u24_e32 v1, 0x300, v4
	v_add_u32_e32 v0, 0x2000, v0
	v_add_lshl_u32 v158, v1, v2, 1
	v_ashrrev_i32_e32 v1, 31, v0
	v_lshrrev_b32_e32 v1, 22, v1
	v_add_u32_e32 v1, v0, v1
	v_ashrrev_i32_e32 v13, 10, v1
	v_mul_i32_i24_e32 v1, 0x400, v13
	v_sub_u32_e32 v0, v0, v1
	v_lshrrev_b32_e32 v1, 4, v0
	v_bitop3_b32 v0, v1, v0, 32 bitop3:0x6c
	v_ashrrev_i32_e32 v2, 31, v0
	v_lshrrev_b32_e32 v2, 26, v2
	v_lshlrev_b32_e32 v1, 3, v13
	v_add_u32_e32 v2, v0, v2
	v_and_b32_e32 v1, -16, v1
	v_ashrrev_i32_e32 v14, 6, v2
	v_lshlrev_b32_e32 v4, 5, v13
	v_and_b32_e32 v2, 0xc0, v2
	s_ashr_i32 s8, s6, 6
	s_ashr_i32 s7, s6, 8
	v_add_u32_e32 v1, v14, v1
	v_and_b32_e32 v15, 32, v4
	v_sub_u32_e32 v0, v0, v2
	v_and_b32_e32 v4, 3, v14
	s_lshl_b32 s2, s8, 10
	s_mul_i32 s1, s70, 0x60000
	v_readlane_b32 s12, v254, 16
	v_ashrrev_i16_sdwa v0, v3, sext(v0) dst_sel:DWORD dst_unused:UNUSED_PAD src0_sel:DWORD src1_sel:BYTE_0
	v_lshlrev_b32_e32 v2, 1, v1
	v_lshrrev_b32_e32 v3, 2, v1
	v_and_or_b32 v4, v1, s0, v4
	s_mul_hi_i32 s0, s70, 0x60000
	v_readlane_b32 s13, v254, 17
	s_add_u32 s12, s12, s1
	v_bfe_i32 v16, v0, 0, 16
	v_and_b32_e32 v2, 24, v2
	v_and_b32_e32 v3, 4, v3
	s_addc_u32 s13, s13, s0
	s_add_i32 s3, s2, 0x110
	v_add_u32_e32 v0, v15, v16
	v_or3_b32 v2, v4, v3, v2
	v_mul_lo_u32 v1, v1, s10
	s_add_i32 m0, s3, 0x10000
	v_add_lshl_u32 v160, v0, v1, 1
	v_mul_u32_u24_e32 v1, 0x300, v2
	global_load_lds_dwordx4 v158, s[12:13]
	s_add_i32 m0, s3, 0x12000
	v_add_lshl_u32 v162, v1, v0, 1
	s_add_u32 s0, s12, 0x30000
	global_load_lds_dwordx4 v162, s[12:13]
	s_addc_u32 s1, s13, 0
	s_add_i32 m0, s3, 0x14000
	s_mul_i32 s5, s71, 0xb0000
	global_load_lds_dwordx4 v158, s[0:1]
	s_add_i32 m0, s3, 0x16000
	s_mul_hi_i32 s4, s71, 0xb0000
	global_load_lds_dwordx4 v162, s[0:1]
	s_add_u32 s0, s98, s5
	s_addc_u32 s1, s99, s4
	s_add_i32 s4, s3, 0x2000
	s_mov_b32 m0, s3
	s_add_u32 s14, s0, 0x58000
	global_load_lds_dwordx4 v156, s[0:1]
	s_mov_b32 m0, s4
	s_addc_u32 s15, s1, 0
	s_add_i32 s5, s3, 0x4000
	global_load_lds_dwordx4 v160, s[0:1]
	s_mov_b32 m0, s5
	s_add_i32 s18, s3, 0x6000
	global_load_lds_dwordx4 v156, s[14:15]
	s_mov_b32 m0, s18
	v_mov_b32_e32 v159, 0
	global_load_lds_dwordx4 v160, s[14:15]
	v_mov_b32_e32 v163, v159
	v_mov_b32_e32 v157, v159
	v_mov_b32_e32 v161, v159
	s_cmp_eq_u32 s7, 1
	s_mov_b32 s11, 0x10000
	v_lshl_add_u64 v[6:7], s[12:13], 0, v[158:159]
	v_lshl_add_u64 v[2:3], s[12:13], 0, v[162:163]
	s_mov_b32 s14, 0x14000
	v_lshl_add_u64 v[0:1], s[0:1], 0, v[156:157]
	s_cselect_b64 s[22:23], -1, 0
	s_cmp_lg_u32 s7, 1
	v_lshl_add_u64 v[4:5], s[0:1], 0, v[160:161]
	s_cbranch_scc1 .LBB0_920
	s_barrier

; template <class Epi, class Sched>
; DI void gemm_phase(PG8_LAS unsigned char* lds, const Gemm g, const Sched& S, const Epi& E) {
;     ...
;   for (;;) {
;     const bool has_next = S.next(ui + 1, nxt);
;     const char* nA = has_next ? (const char*)g.A + (size_t)nxt.pm * tstepA : cA; const char* nB = has_next ? (const char*)g.Bt + (size_t)nxt.pn * tstepB : cB;
; #pragma unroll 1
;     for (int t = 0; t < nt; t += 2) {
;       const bool last = (t == nt - 2);
;       const char* a1 = cA + (size_t)(t + 1) * kstep;
;       const char* a2 = last ? nA : cA + (size_t)(t + 2) * kstep; const char* b2 = last ? nB : cB + (size_t)(t + 2) * kstep;
;       const char* a3 = a2 + kstep; const char* b3 = b2 + kstep;
.LBB0_925:
	v_cndmask_b32_e64 v0, 0, 1, s[14:15]
	v_cmp_ne_u32_e64 s[10:11], 1, v0
	s_andn2_b64 vcc, exec, s[14:15]
	s_mov_b64 s[34:35], s[0:1]
	s_cbranch_vccnz .LBB0_927
	s_mul_i32 s15, s69, 0xb0000
	s_mul_hi_i32 s14, s69, 0xb0000
	s_add_u32 s34, s98, s15
	s_addc_u32 s35, s99, s14

; #define PG8_STAGE(bufoff, gbase, voff) do { _Pragma("unroll") for (int _i = 0; _i < 2; ++_i) \
;     __builtin_amdgcn_global_load_lds((const unsigned*)((const char*)(gbase) + (voff)[_i]), (PG8_LAS unsigned*)(lds + (bufoff) + ldsw + _i * 8192), 16, 0, 0); } while (0)
; #define PG8_WAIT_V(n) asm volatile("s_waitcnt vmcnt(" #n ")" ::: "memory")
; #define PG8_BAR __builtin_amdgcn_s_barrier()
; template <class Epi, class Sched>
; DI void gemm_phase(PG8_LAS unsigned char* lds, const Gemm g, const Sched& S, const Epi& E) {
;     ...
;   for (int i = 0; i < 2; ++i) { int R, C; stage_rc(tid * 16 + i * 8192, R, C); const int Rb = Epi::PERM ? ((R & ~31) + perm32(R & 31)) : R;
;     voffA[i] = (unsigned)(R * g.lda + C) * 2u; voffB[i] = (unsigned)(Rb * K + C) * 2u; }
;   const size_t kstep = (size_t)(BK * 2);
;   const size_t hstepA = (size_t)HALF * g.lda * 2, hstepB = (size_t)HALF * K * 2;
;   const size_t tstepA = 2 * hstepA, tstepB = 2 * hstepB;
;   const unsigned ldsw = (unsigned)wid * 1024u;
;   const int aoff = lds_byte(wr * 64 + fr, fq * 8), boff = lds_byte(wc * 32 + fr, fq * 8);
;     ...
;   Unit cur, nxt; int ui = 0;
;   if (!S.next(0, cur)) return;
;   f32x4 acc[2][2][4][2];
; #pragma unroll
;   for (int a = 0; a < 2; ++a)
; #pragma unroll
;     for (int b = 0; b < 2; ++b)
; #pragma unroll
;       for (int m = 0; m < 4; ++m)
; #pragma unroll
;         for (int n = 0; n < 2; ++n) acc[a][b][m][n] = (f32x4){0.f, 0.f, 0.f, 0.f};
;   bf16x8 At[4][2], B0[2][2], B1[2][2];
;   const char* cA = (const char*)g.A + (size_t)cur.pm * tstepA; const char* cB = (const char*)g.Bt + (size_t)cur.pn * tstepB;
;   PG8_STAGE(PG8_SB(0, 0), cB, voffB); PG8_STAGE(PG8_SB(0, 1), cB + hstepB, voffB); PG8_STAGE(PG8_SA(0, 0), cA, voffA); PG8_STAGE(PG8_SA(0, 1), cA + hstepA, voffA);
;   if (wr == 1) PG8_BAR;
;   PG8_WAIT_V(2); PG8_BAR;
;   PG8_STAGE(PG8_SB(1, 0), cB + kstep, voffB); PG8_STAGE(PG8_SA(1, 0), cA + kstep, voffA); PG8_STAGE(PG8_SB(1, 1), cB + hstepB + kstep, voffB);
;   PG8_WAIT_V(6); PG8_BAR;
; __global__ void __launch_bounds__(NTHREADS, 2) fwd_megakernel(Params p) {
;     ...
;     pg8::Gemm g2{(const bf16_t*)(ws + O_PM) + 768, 1408, (const bf16_t*)(ws + O_KVUP), T_TOK, 1536, 256};
;     pg8::XOrder S2; S2.init(T_TOK, 1536, toff);
;     pg8::EpiNorm<pg8::EM_KVUP> E2{(bf16_t*)(ws + O_KN), 1152, 1536, (bf16_t*)(ws + O_V1), ps2, 12, 16, 1.f / 256.f, nullptr};
;     pg8::gemm_phase(lds, g2, S2, E2);
.LBB0_973:
	s_add_u32 s14, s86, 0x107a4000
	s_addc_u32 s15, s87, 0
	s_add_u32 s22, s86, 0x14fa4000
	s_addc_u32 s23, s87, 0
	s_andn2_b64 vcc, exec, s[6:7]
	s_cbranch_vccnz .LBB0_1057
	v_bfe_i32 v2, v8, 27, 1
	v_lshlrev_b32_e32 v0, 4, v8
	v_lshrrev_b32_e32 v2, 22, v2
	v_add_u32_e32 v2, v0, v2
	v_and_b32_e32 v2, 0xfffffc00, v2
	v_sub_u32_e32 v2, v0, v2
	v_lshrrev_b32_e32 v3, 4, v2
	v_ashrrev_i32_e32 v1, 31, v8
	v_bitop3_b32 v3, v3, v2, 32 bitop3:0x6c
	v_ashrrev_i32_e32 v2, 31, v2
	v_lshrrev_b32_e32 v1, 26, v1
	v_lshrrev_b32_e32 v2, 26, v2
	v_add_u32_e32 v1, v8, v1
	v_add_u32_e32 v2, v3, v2
	v_ashrrev_i32_e32 v1, 6, v1
	v_ashrrev_i32_e32 v2, 6, v2
	v_lshlrev_b32_e32 v4, 3, v1
	v_mul_i32_i24_e32 v5, 64, v2
	v_and_b32_e32 v4, -16, v4
	v_lshlrev_b32_e32 v1, 5, v1
	v_sub_u32_e32 v3, v3, v5
	v_mov_b32_e32 v5, 1
	v_add_u32_e32 v4, v2, v4
	v_and_b32_e32 v1, 32, v1
	v_ashrrev_i16_sdwa v3, v5, sext(v3) dst_sel:DWORD dst_unused:UNUSED_PAD src0_sel:DWORD src1_sel:BYTE_0
	v_add_u32_sdwa v1, v1, sext(v3) dst_sel:DWORD dst_unused:UNUSED_PAD src0_sel:DWORD src1_sel:WORD_0
	v_lshlrev_b32_e32 v3, 1, v4
	v_lshrrev_b32_e32 v6, 2, v4
	v_and_b32_e32 v2, 3, v2
	s_mov_b32 s1, 0x7fffe0
	v_and_b32_e32 v3, 24, v3
	v_and_b32_e32 v6, 4, v6
	v_and_or_b32 v2, v4, s1, v2
	s_movk_i32 s7, 0x580
	v_or3_b32 v2, v2, v6, v3
	v_mul_lo_u32 v3, v4, s7
	v_add_lshl_u32 v156, v1, v3, 1
	v_lshlrev_b32_e32 v1, 1, v1
	v_add_u32_e32 v0, 0x2000, v0
	v_lshl_add_u32 v158, v2, 9, v1
	v_ashrrev_i32_e32 v1, 31, v0
	v_lshrrev_b32_e32 v1, 22, v1
	v_add_u32_e32 v1, v0, v1
	v_ashrrev_i32_e32 v1, 10, v1
	v_mul_i32_i24_e32 v2, 0x400, v1
	v_sub_u32_e32 v0, v0, v2
	v_lshrrev_b32_e32 v2, 4, v0
	v_bitop3_b32 v0, v2, v0, 32 bitop3:0x6c
	v_ashrrev_i32_e32 v3, 31, v0
	v_lshrrev_b32_e32 v3, 26, v3
	v_lshlrev_b32_e32 v2, 3, v1
	v_add_u32_e32 v3, v0, v3
	v_and_b32_e32 v2, -16, v2
	v_ashrrev_i32_e32 v4, 6, v3
	v_and_b32_e32 v3, 0xc0, v3
	s_add_u32 s3, s86, 0x17fa4600
	v_add_u32_e32 v2, v4, v2
	v_lshlrev_b32_e32 v1, 5, v1
	v_sub_u32_e32 v0, v0, v3
	v_and_b32_e32 v4, 3, v4
	s_addc_u32 s53, s87, 0
	s_ashr_i32 s6, s4, 6
	v_and_b32_e32 v1, 32, v1
	v_ashrrev_i16_sdwa v0, v5, sext(v0) dst_sel:DWORD dst_unused:UNUSED_PAD src0_sel:DWORD src1_sel:BYTE_0
	v_and_or_b32 v4, v2, s1, v4
	s_ashr_i32 s1, s0, 31
	v_add_u32_sdwa v0, v1, sext(v0) dst_sel:DWORD dst_unused:UNUSED_PAD src0_sel:DWORD src1_sel:WORD_0
	v_lshlrev_b32_e32 v1, 1, v2
	v_lshrrev_b32_e32 v3, 2, v2
	v_mul_lo_u32 v2, v2, s7
	s_ashr_i32 s7, s4, 8
	s_lshl_b32 s55, s6, 10
	s_lshl_b64 s[8:9], s[0:1], 17
	s_add_u32 s10, s62, s8
	s_addc_u32 s11, s63, s9
	s_add_i32 s68, s55, 0x110
	v_and_b32_e32 v1, 24, v1
	v_and_b32_e32 v3, 4, v3
	s_add_i32 m0, s68, 0x10000
	v_or3_b32 v1, v4, v3, v1
	v_add_lshl_u32 v160, v0, v2, 1
	v_lshlrev_b32_e32 v0, 1, v0
	global_load_lds_dwordx4 v158, s[10:11]
	s_add_i32 m0, s68, 0x12000
	v_lshl_add_u32 v162, v1, 9, v0
	s_add_u32 s8, s10, 0x10000
	global_load_lds_dwordx4 v162, s[10:11]
	s_addc_u32 s9, s11, 0
	s_add_i32 m0, s68, 0x14000
	s_mul_i32 s12, s5, 0xb0000
	global_load_lds_dwordx4 v158, s[8:9]
	s_add_i32 m0, s68, 0x16000
	s_mul_hi_i32 s13, s5, 0xb0000
	s_add_u32 s12, s3, s12
	s_addc_u32 s13, s53, s13
	s_add_i32 s69, s68, 0x2000
	global_load_lds_dwordx4 v162, s[8:9]
	s_mov_b32 m0, s68
	s_add_u32 s8, s12, 0x58000
	global_load_lds_dwordx4 v156, s[12:13]
	s_mov_b32 m0, s69
	s_addc_u32 s9, s13, 0
	s_add_i32 s79, s68, 0x4000
	global_load_lds_dwordx4 v160, s[12:13]
	s_mov_b32 m0, s79
	s_add_i32 s90, s68, 0x6000
	global_load_lds_dwordx4 v156, s[8:9]
	s_mov_b32 m0, s90
	v_mov_b32_e32 v165, 0
	global_load_lds_dwordx4 v160, s[8:9]
	s_cmp_eq_u32 s7, 1
	v_mov_b32_e32 v159, v165
	v_mov_b32_e32 v163, v165
	v_mov_b32_e32 v157, v165
	v_mov_b32_e32 v161, v165
	s_cselect_b64 s[16:17], -1, 0
	s_mov_b32 s1, 0x10000
	v_lshl_add_u64 v[4:5], s[10:11], 0, v[158:159]
	v_lshl_add_u64 v[2:3], s[10:11], 0, v[162:163]
	s_mov_b32 s8, 0x14000
	v_lshl_add_u64 v[0:1], s[12:13], 0, v[156:157]
	v_writelane_b32 v254, s16, 12
	s_cmp_lg_u32 s7, 1
	v_lshl_add_u64 v[6:7], s[12:13], 0, v[160:161]
	v_writelane_b32 v254, s17, 13
	s_cbranch_scc1 .LBB0_976
	s_barrier

; DI int launder_tid() { int t = threadIdx.x; asm volatile("" : "+v"(t)); return t; }
; template <int D, bool ROPE>
; DI void headnorm_phase(const bf16_t* src1, int ld1, int hs1, const bf16_t* src2, int ld2, int hs2, bf16_t* dst, int ldd, int hsd,
;                        const float* __restrict__ gain, int nrows, int nheads, const int* __restrict__ pos, float oscale) {
;     ...
;   const int tidh = launder_tid();
;   const int s = tidh & 15;
;   const long nitems = (long)nrows * nheads;
;   const long stride = (long)gridDim.x * (NTHREADS / 16);
;   float gn[NM];
; #pragma unroll
;   for (int m = 0; m < NM; ++m) gn[m] = gain[s + 16 * m] * oscale;
;   const float invf = ROPE ? exp2f(-(float)s * (13.287712379549449f / 16.f)) : 0.f;
;   for (long it0 = (long)blockIdx.x * (NTHREADS / 16) + (tidh >> 4); it0 < nitems; it0 += stride * U) {
; __global__ void __launch_bounds__(NTHREADS, 2) fwd_megakernel(Params p) {
;     ...
;   {
;     bf16_t* kn = (bf16_t*)(ws + O_KN); bf16_t* pm = (bf16_t*)(ws + O_PM);
;     headnorm_phase<96, true>(kn, 1152, 96, pm + 1024, 1408, 0, kn, 1152, 96, p.mla_g_kn, T_TOK, 12, p.pos, 1.f);
;   }
.LBB0_1109:
	s_or_b64 exec, exec, s[0:1]
	v_readlane_b32 s12, v254, 20
	v_mov_b32_e32 v0, v212
	v_readlane_b32 s13, v254, 21
	s_waitcnt lgkmcnt(0)
	s_barrier
	s_mov_b64 s[6:7], exec
	v_and_b32_e32 v1, 63, v0
	v_lshrrev_b32_e32 v2, 6, v0
	v_and_b32_e32 v3, 7, v1
	v_lshrrev_b32_e32 v4, 3, v1
	v_lshlrev_b32_e32 v5, 5, v3
	v_readfirstlane_b32 s0, v2
	global_load_dwordx4 v[8:11], v5, s[82:83]
	global_load_dwordx4 v[12:15], v5, s[82:83] offset:16
	v_lshlrev_b32_e32 v6, 3, v3
	global_load_dwordx2 v[16:17], v6, s[82:83] offset:256
	global_load_dwordx2 v[18:19], v6, s[82:83] offset:320
	v_lshlrev_b32_e32 v7, 1, v3
	v_cvt_f32_u32_e32 v20, v7
	v_add_f32_e32 v21, 1.0, v20
	v_mul_f32_e32 v20, 0xbf549a78, v20
	v_mul_f32_e32 v21, 0xbf549a78, v21
	v_exp_f32_e32 v20, v20
	v_exp_f32_e32 v21, v21
	v_lshlrev_b32_e32 v22, 4, v3
	v_lshlrev_b32_e32 v23, 2, v3
	v_mov_b32_e32 v24, 0x358637bd
	s_and_b32 s13, s12, 7
	s_mul_i32 s13, s13, 0xc000
	v_add_u32_e32 v4, s13, v4
	s_lshr_b32 s1, s12, 3
	s_lshl_b32 s1, s1, 3
	s_add_i32 s1, s1, s0
	s_lshl_b32 s1, s1, 5
	s_lshl_b32 s2, s88, 5
	s_mov_b32 s3, 0x3c2aaaab
	s_mov_b32 s18, 0xaaaaaaab
	s_movk_i32 s19, 0xc0
	s_add_u32 s8, s86, 0x107a4000
	s_addc_u32 s9, s87, 0
	s_add_u32 s10, s86, 0x17fa4800
	s_addc_u32 s11, s87, 0
	s_waitcnt vmcnt(0)

; DI int launder_tid() { int t = threadIdx.x; asm volatile("" : "+v"(t)); return t; }
; DI float bf2f(bf16_t v) { return __uint_as_float(((unsigned)v) << 16); }
; template <int DQK, int MODE, bool QN, bool KN> ...
;     ...
;   const int tid = launder_tid(), lane = tid & 63, wave = tid >> 6, r = lane & 31, h = lane >> 5;
;   const int qrow = q0 + wave * 32 + r;
;   const int qwmax = q0 + wave * 32 + 31;
;   bf16x8 qf[NS];
; #pragma unroll
;   for (int s = 0; s < NS; ++s) qf[s] = *(const bf16x8*)(Q + (size_t)(wave * 32 + r) * ldq + 16 * s + 8 * h);
;   if (QN) {
;     float qv[NS][8];
;     float ss = 0.f;
; #pragma unroll
;     for (int s = 0; s < NS; ++s)
; #pragma unroll
;       for (int j = 0; j < 8; ++j) { qv[s][j] = bf2f((bf16_t)qf[s][j]); ss += qv[s][j] * qv[s][j]; }
;     ss += __shfl_xor(ss, 32);
;     const float rstd = rsqrtf(ss * (1.f / DQK) + EPS) * oscale;
; #pragma unroll
;     for (int s = 0; s < NS; ++s) {
;       const f32x4 g0 = *(const f32x4*)(gq + 16 * s + 8 * h), g1 = *(const f32x4*)(gq + 16 * s + 8 * h + 4);
; #pragma unroll
;       for (int j = 0; j < 4; ++j) { qv[s][j] *= rstd * g0[j]; qv[s][4 + j] *= rstd * g1[j]; }
;     }
; template <int LAYER>
; DI void attn_phase(const Params& p, char* smem) {
;     ...
;       const int j2 = j - 192, qt = j2 & 15, hm = j2 >> 4, b = xcd, q0 = qt * 256;
;       const size_t tok0 = (size_t)b * SEQ;
;       bf16_t* O = mix + (tok0 + q0) * DM + 768 + hm * 64;
;       const bf16_t* KR = (const bf16_t*)(ws + O_KMRAW) + (size_t)LAYER * 2048 * 512 + (size_t)(b * 256) * 512 + hm * 128;
;       const bf16_t* Qm = LAYER == 0 ? (const bf16_t*)(ws + O_P) + (tok0 + q0) * 2560 + 2304 + hm * 64 : (const bf16_t*)(ws + O_PM) + (tok0 + q0) * 1408 + 1056 + hm * 64;
;       attn_item<64, 0, true, true>(Qm, LAYER == 0 ? 2560 : 1408, KR, 512, KR + 64, 512, q0, 4, O, 1.f, smem,
;                                    p.g_qn_mem + LAYER * 64, 0.18033688011112042f, nullptr, p.g_kn_mem + LAYER * 64);
.LBB0_1168:
	s_cmpk_gt_u32 s54, 0xbf
	s_mov_b64 s[0:1], -1
	s_cbranch_scc0 .LBB0_1194
	s_add_i32 s0, s54, 0xffffff40
	s_lshr_b32 s13, s0, 4
	s_lshl_b32 s0, s54, 8
	s_and_b32 s0, s0, 0xf00
	s_lshl_b32 s6, s13, 7
	s_or_b32 s12, s0, s9
	s_lshl_b64 s[0:1], s[6:7], 1
	s_add_u32 s0, s24, s0
	s_addc_u32 s1, s25, s1
	s_mul_i32 s2, s12, 0xb00
	s_add_u32 s2, s86, s2
	s_addc_u32 s3, s87, 0
	s_add_u32 s2, s2, s6
	s_addc_u32 s3, s3, 0
	s_add_u32 s2, s2, 0x17fa4840
	v_mov_b32_e32 v51, v212
	s_addc_u32 s3, s3, 0
	v_mov_b64_e32 v[2:3], s[2:3]
	v_ashrrev_i32_e32 v0, 1, v51
	v_bfe_u32 v204, v51, 5, 1
	s_waitcnt vmcnt(8)
	v_bfi_b32 v202, s27, v0, v51
	v_mad_i64_i32 v[2:3], s[2:3], v202, s26, v[2:3]
	v_lshlrev_b32_e32 v0, 4, v204
	v_lshl_add_u64 v[2:3], v[2:3], 0, v[0:1]
	global_load_dwordx4 v[38:41], v[2:3], off offset:96
	global_load_dwordx4 v[42:45], v[2:3], off offset:64
	global_load_dwordx4 v[46:49], v[2:3], off offset:32
	global_load_dwordx4 v[34:37], v[2:3], off
	v_cmp_lt_i32_e32 vcc, v227, v228
	s_waitcnt vmcnt(12)
	v_lshlrev_b32_e32 v108, 5, v204
	v_add_u32_e32 v0, 0x110, v0
	v_cndmask_b32_e32 v2, v226, v227, vcc
	v_lshlrev_b32_e32 v205, 2, v2
	global_load_dwordx4 v[30:33], v108, s[58:59] offset:256
	global_load_dwordx4 v[26:29], v108, s[58:59] offset:272
	global_load_dwordx4 v[22:25], v108, s[58:59] offset:320
	global_load_dwordx4 v[18:21], v108, s[58:59] offset:336
	global_load_dwordx4 v[14:17], v108, s[58:59] offset:384
	global_load_dwordx4 v[10:13], v108, s[58:59] offset:400
	global_load_dwordx4 v[6:9], v108, s[58:59] offset:448
	global_load_dwordx4 v[2:5], v108, s[58:59] offset:464
	global_load_dwordx4 v[52:55], v108, s[60:61] offset:272
	global_load_dwordx4 v[56:59], v108, s[60:61] offset:256
	s_mov_b64 s[2:3], -1
	s_waitcnt vmcnt(13)
	v_and_b32_e32 v75, 0xffff0000, v38
	s_waitcnt vmcnt(12)
	v_and_b32_e32 v77, 0xffff0000, v45
	v_lshlrev_b32_e32 v76, 16, v45
	s_waitcnt vmcnt(10)
	v_and_b32_e32 v83, 0xffff0000, v34
	v_lshlrev_b32_e32 v82, 16, v34
	v_and_b32_e32 v81, 0xffff0000, v35
	v_lshlrev_b32_e32 v80, 16, v35
	v_pk_mul_f32 v[106:107], v[82:83], v[82:83]
	v_pk_mul_f32 v[104:105], v[80:81], v[80:81]
	v_add_f32_e32 v50, v106, v107
	v_and_b32_e32 v79, 0xffff0000, v36
	v_lshlrev_b32_e32 v78, 16, v36
	v_add_f32_e32 v50, v104, v50
	v_pk_mul_f32 v[102:103], v[78:79], v[78:79]
	v_add_f32_e32 v50, v105, v50
	v_and_b32_e32 v67, 0xffff0000, v37
	v_lshlrev_b32_e32 v66, 16, v37
	v_add_f32_e32 v50, v102, v50
	v_pk_mul_f32 v[100:101], v[66:67], v[66:67]
	v_add_f32_e32 v50, v103, v50
	v_and_b32_e32 v61, 0xffff0000, v44
	v_lshlrev_b32_e32 v60, 16, v44
	v_and_b32_e32 v63, 0xffff0000, v43
	v_lshlrev_b32_e32 v62, 16, v43
	v_and_b32_e32 v65, 0xffff0000, v42
	v_lshlrev_b32_e32 v64, 16, v42
	v_and_b32_e32 v43, 0xffff0000, v49
	v_lshlrev_b32_e32 v42, 16, v49
	v_and_b32_e32 v45, 0xffff0000, v48
	v_lshlrev_b32_e32 v44, 16, v48
	v_and_b32_e32 v49, 0xffff0000, v47
	v_lshlrev_b32_e32 v48, 16, v47
	v_and_b32_e32 v47, 0xffff0000, v46
	v_lshlrev_b32_e32 v46, 16, v46
	v_add_f32_e32 v50, v100, v50
	v_pk_mul_f32 v[98:99], v[46:47], v[46:47]
	v_add_f32_e32 v50, v101, v50
	v_add_f32_e32 v50, v98, v50
	v_pk_mul_f32 v[96:97], v[48:49], v[48:49]
	v_add_f32_e32 v50, v99, v50
	v_add_f32_e32 v50, v96, v50
	v_pk_mul_f32 v[94:95], v[44:45], v[44:45]
	v_add_f32_e32 v50, v97, v50
	v_add_f32_e32 v50, v94, v50
	v_pk_mul_f32 v[92:93], v[42:43], v[42:43]
	v_add_f32_e32 v50, v95, v50
	v_add_f32_e32 v50, v92, v50
	v_pk_mul_f32 v[90:91], v[64:65], v[64:65]
	v_add_f32_e32 v50, v93, v50
	v_add_f32_e32 v50, v90, v50
	v_pk_mul_f32 v[88:89], v[62:63], v[62:63]
	v_add_f32_e32 v50, v91, v50
	v_add_f32_e32 v50, v88, v50
	v_pk_mul_f32 v[86:87], v[60:61], v[60:61]
	v_add_f32_e32 v50, v89, v50
	v_add_f32_e32 v50, v86, v50
	v_pk_mul_f32 v[84:85], v[76:77], v[76:77]
	v_add_f32_e32 v50, v87, v50
	v_lshlrev_b32_e32 v74, 16, v38
	v_add_f32_e32 v50, v84, v50
	v_and_b32_e32 v69, 0xffff0000, v41
	v_lshlrev_b32_e32 v68, 16, v41
	v_and_b32_e32 v71, 0xffff0000, v40
	v_lshlrev_b32_e32 v70, 16, v40
	v_pk_mul_f32 v[40:41], v[74:75], v[74:75]
	v_add_f32_e32 v50, v85, v50
	v_and_b32_e32 v73, 0xffff0000, v39
	v_lshlrev_b32_e32 v72, 16, v39
	v_add_f32_e32 v40, v40, v50
	v_pk_mul_f32 v[38:39], v[72:73], v[72:73]
	v_add_f32_e32 v40, v41, v40
	v_add_f32_e32 v38, v38, v40
	v_pk_mul_f32 v[36:37], v[70:71], v[70:71]
	v_add_f32_e32 v38, v39, v38
	v_add_f32_e32 v36, v36, v38
	v_pk_mul_f32 v[34:35], v[68:69], v[68:69]
	v_add_f32_e32 v36, v37, v36
	v_add_f32_e32 v34, v34, v36
	v_add_f32_e32 v38, v35, v34
	global_load_dwordx4 v[34:37], v108, s[60:61] offset:320
	ds_bpermute_b32 v39, v205, v38
	v_and_b32_e32 v98, 31, v51
	s_waitcnt lgkmcnt(0)
	v_add_f32_e32 v38, v38, v39
	v_fmamk_f32 v38, v38, 0x3c800000, v214
	v_mul_f32_e32 v39, 0x4b800000, v38
	v_cmp_gt_f32_e32 vcc, s28, v38
	s_nop 1
	v_cndmask_b32_e32 v38, v38, v39, vcc
	v_rsq_f32_e32 v50, v38
	global_load_dwordx4 v[38:41], v108, s[60:61] offset:336
	v_mul_f32_e32 v84, 0x45800000, v50
	v_cndmask_b32_e32 v50, v50, v84, vcc
	v_mul_f32_e32 v50, 0x3e38aa3b, v50
	s_waitcnt vmcnt(10)
	v_pk_mul_f32 v[86:87], v[26:27], v[50:51] op_sel_hi:[1,0]
	s_waitcnt vmcnt(9)
	v_pk_mul_f32 v[92:93], v[22:23], v[50:51] op_sel_hi:[1,0]
	v_pk_mul_f32 v[88:89], v[32:33], v[50:51] op_sel_hi:[1,0]
	v_pk_mul_f32 v[78:79], v[86:87], v[78:79]
	v_pk_mul_f32 v[86:87], v[92:93], v[46:47]
	s_waitcnt vmcnt(8)
	v_pk_mul_f32 v[46:47], v[18:19], v[50:51] op_sel_hi:[1,0]
	v_pk_mul_f32 v[84:85], v[30:31], v[50:51] op_sel_hi:[1,0]
	v_pk_mul_f32 v[90:91], v[28:29], v[50:51] op_sel_hi:[1,0]
	v_pk_mul_f32 v[80:81], v[88:89], v[80:81]
	v_pk_mul_f32 v[88:89], v[46:47], v[44:45]
	v_pk_mul_f32 v[44:45], v[24:25], v[50:51] op_sel_hi:[1,0]
	v_pk_mul_f32 v[82:83], v[84:85], v[82:83]
	v_pk_mul_f32 v[84:85], v[90:91], v[66:67]
	v_pk_mul_f32 v[90:91], v[44:45], v[48:49]
	v_pk_mul_f32 v[44:45], v[20:21], v[50:51] op_sel_hi:[1,0]
	s_waitcnt vmcnt(7)
; template <int DQK, int MODE, bool QN, bool KN> ...
;     ...
;     const float rstd = rsqrtf(ss * (1.f / DQK) + EPS) * oscale;
; #pragma unroll
;     for (int s = 0; s < NS; ++s) {
;       const f32x4 g0 = *(const f32x4*)(gq + 16 * s + 8 * h), g1 = *(const f32x4*)(gq + 16 * s + 8 * h + 4);
; #pragma unroll
;       for (int j = 0; j < 4; ++j) { qv[s][j] *= rstd * g0[j]; qv[s][4 + j] *= rstd * g1[j]; }
;     }
;     if (DQK == 96) {
;       const float pf_ = (float)qpos[wave * 32 + r];
; #pragma unroll
;       for (int j = 0; j < 8; ++j) {
;         const float ang = pf_ * exp2f(-(float)(8 * h + j) * (13.287712379549449f / 16.f));
;         float rev = ang * 0.15915494309189535f; rev = rev - floorf(rev);
;         const float sn = __builtin_amdgcn_sinf(rev), cs = __builtin_amdgcn_cosf(rev);
;         const float x1 = qv[NS - 2][j], x2 = qv[NS - 1][j];
;         qv[NS - 2][j] = x1 * cs - x2 * sn; qv[NS - 1][j] = x2 * cs + x1 * sn;
;       }
;     }
; #pragma unroll
;     for (int s = 0; s < NS; ++s) {
;       u32x4 w; w.x = pack2(qv[s][0], qv[s][1]); w.y = pack2(qv[s][2], qv[s][3]); w.z = pack2(qv[s][4], qv[s][5]); w.w = pack2(qv[s][6], qv[s][7]);
;       qf[s] = __builtin_bit_cast(bf16x8, w);
;     }
;   }
;   f32x4 gk0 = {1.f, 1.f, 1.f, 1.f}, gk1 = {1.f, 1.f, 1.f, 1.f};
;   if (KN) { gk0 = *(const f32x4*)(gk + (tid & 7) * 8); gk1 = *(const f32x4*)(gk + (tid & 7) * 8 + 4); }
;   float sbound = 0.f; bool fixed_shift = false;
;   if (MODE != 2 && QN) {
;     float gqm = 0.f, gkm = 0.f;
; #pragma unroll
;     for (int s = 0; s < NS; ++s)
; #pragma unroll
;       for (int j = 0; j < 8; ++j) { gqm = fmaxf(gqm, fabsf(gq[16 * s + 8 * h + j])); gkm = fmaxf(gkm, fabsf(gk[16 * s + 8 * h + j])); }
;     gqm = fmaxf(gqm, __shfl_xor(gqm, 32)); gkm = fmaxf(gkm, __shfl_xor(gkm, 32));
;     sbound = sqrtf((float)DQK) * 1.4426950408889634f * gqm * gkm * 1.02f + 0.01f;
;     fixed_shift = __builtin_amdgcn_readfirstlane(sbound < 48.f ? 1 : 0) != 0;
;   }
;   f32x16 o[2];
; #pragma unroll
;   for (int a = 0; a < 2; ++a)
; #pragma unroll
;     for (int i = 0; i < 16; ++i) o[a][i] = 0.f;
;   float m_run = -INFINITY, l_run = 0.f, carry = 1.f;
;   u32x4 rk0[NKL], rv0[2], rk1[NKL], rv1[2];
;   const int vtr_off = (4 * h + ((lane & 15) >> 2)) * 64 + (((lane >> 4) & 1) * 16 + 4 * (lane & 3)) * 2;
	v_pk_mul_f32 v[66:67], v[14:15], v[50:51] op_sel_hi:[1,0]
	v_pk_mul_f32 v[92:93], v[44:45], v[42:43]
	global_load_dwordx4 v[42:45], v108, s[60:61] offset:400
	global_load_dwordx4 v[46:49], v108, s[60:61] offset:384
	v_pk_mul_f32 v[94:95], v[66:67], v[64:65]
	s_waitcnt vmcnt(8)
	v_pk_mul_f32 v[64:65], v[10:11], v[50:51] op_sel_hi:[1,0]
	v_max3_f32 v30, |v30|, 0, |v31|
	v_pk_mul_f32 v[96:97], v[64:65], v[60:61]
	v_pk_mul_f32 v[60:61], v[16:17], v[50:51] op_sel_hi:[1,0]
	s_waitcnt vmcnt(4)
	v_max3_f32 v31, |v56|, 0, |v57|
	v_pk_mul_f32 v[100:101], v[60:61], v[62:63]
	global_load_dwordx4 v[60:63], v108, s[60:61] offset:464
	global_load_dwordx4 v[64:67], v108, s[60:61] offset:448
	v_max3_f32 v30, v30, |v32|, |v33|
	v_max3_f32 v31, v31, |v58|, |v59|
	v_max3_f32 v26, v30, |v26|, |v27|
	v_max3_f32 v27, v31, |v52|, |v53|
	v_max3_f32 v26, v26, |v28|, |v29|
	v_max3_f32 v27, v27, |v54|, |v55|
	v_max3_f32 v22, v26, |v22|, |v23|
	v_max3_f32 v22, v22, |v24|, |v25|
	v_pk_mul_f32 v[102:103], v[12:13], v[50:51] op_sel_hi:[1,0]
	v_cvt_pk_bf16_f32 v174, v82, v83
	v_pk_mul_f32 v[76:77], v[102:103], v[76:77]
	v_pk_mul_f32 v[102:103], v[6:7], v[50:51] op_sel_hi:[1,0]
	v_cvt_pk_bf16_f32 v175, v80, v81
	v_pk_mul_f32 v[74:75], v[102:103], v[74:75]
	v_pk_mul_f32 v[102:103], v[2:3], v[50:51] op_sel_hi:[1,0]
	v_cvt_pk_bf16_f32 v176, v78, v79
	v_pk_mul_f32 v[70:71], v[102:103], v[70:71]
	v_pk_mul_f32 v[102:103], v[8:9], v[50:51] op_sel_hi:[1,0]
	v_cvt_pk_bf16_f32 v177, v84, v85
	v_pk_mul_f32 v[72:73], v[102:103], v[72:73]
	v_pk_mul_f32 v[102:103], v[4:5], v[50:51] op_sel_hi:[1,0]
	v_lshlrev_b32_e32 v50, 3, v51
	v_pk_mul_f32 v[68:69], v[102:103], v[68:69]
	v_cvt_pk_bf16_f32 v182, v86, v87
	v_cvt_pk_bf16_f32 v173, v68, v69
	v_and_b32_e32 v69, 56, v50
	v_lshlrev_b32_e32 v68, 2, v69
	v_cvt_pk_bf16_f32 v183, v90, v91
	v_cvt_pk_bf16_f32 v184, v88, v89
	v_cvt_pk_bf16_f32 v185, v92, v93
	v_cvt_pk_bf16_f32 v178, v94, v95
	v_cvt_pk_bf16_f32 v179, v100, v101
	v_cvt_pk_bf16_f32 v180, v96, v97
	v_cvt_pk_bf16_f32 v181, v76, v77
	s_waitcnt vmcnt(5)
	v_max3_f32 v23, v27, |v34|, |v35|
	v_max3_f32 v36, v23, |v36|, |v37|
	v_max3_f32 v37, v22, |v18|, |v19|
	v_ashrrev_i32_e32 v18, 31, v51
	v_lshrrev_b32_e32 v18, 29, v18
	v_add_u32_e32 v18, v51, v18
	v_ashrrev_i32_e32 v30, 3, v18
	v_ashrrev_i32_e32 v31, 31, v30
	v_lshlrev_b32_e32 v22, 6, v30
	v_lshlrev_b64 v[18:19], 10, v[30:31]
	v_sub_u32_e32 v22, v50, v22
	v_lshl_add_u64 v[18:19], s[0:1], 0, v[18:19]
	v_ashrrev_i32_e32 v23, 31, v22
	v_add_u32_e32 v31, 0x200, v51
	v_lshl_add_u64 v[32:33], v[22:23], 1, v[18:19]
	v_ashrrev_i32_e32 v18, 31, v31
	v_lshrrev_b32_e32 v18, 29, v18
	v_add_u32_e32 v18, v31, v18
	v_ashrrev_i32_e32 v18, 3, v18
	v_ashrrev_i32_e32 v19, 31, v18
	v_lshlrev_b64 v[26:27], 10, v[18:19]
	v_lshlrev_b32_e32 v19, 6, v18
	v_lshlrev_b32_e32 v28, 3, v31
	v_sub_u32_e32 v28, v28, v19
	v_lshl_add_u64 v[26:27], s[0:1], 0, v[26:27]
	v_ashrrev_i32_e32 v29, 31, v28
	v_lshl_add_u64 v[34:35], v[28:29], 1, v[26:27]
	global_load_dwordx4 v[22:25], v[32:33], off
	global_load_dwordx4 v[26:29], v[34:35], off
	s_waitcnt vmcnt(6)
	v_max3_f32 v19, v36, |v38|, |v39|
	v_max3_f32 v20, v37, |v20|, |v21|
	v_max3_f32 v19, v19, |v40|, |v41|
	v_max3_f32 v14, v20, |v14|, |v15|
	v_max3_f32 v14, v14, |v16|, |v17|
	v_max3_f32 v10, v14, |v10|, |v11|
	v_max3_f32 v10, v10, |v12|, |v13|
	v_max3_f32 v6, v10, |v6|, |v7|
	s_waitcnt vmcnt(4)
	v_max3_f32 v15, v19, |v46|, |v47|
	v_max3_f32 v15, v15, |v48|, |v49|
	v_max3_f32 v11, v15, |v42|, |v43|
	v_max3_f32 v11, v11, |v44|, |v45|
	v_max3_f32 v6, v6, |v8|, |v9|
	v_max3_f32 v2, v6, |v2|, |v3|
	global_load_dwordx4 v[146:149], v68, s[60:61] offset:272
	global_load_dwordx4 v[150:153], v68, s[60:61] offset:256
	v_max3_f32 v2, v2, |v4|, |v5|
	s_waitcnt vmcnt(4)
	v_max3_f32 v7, v11, |v64|, |v65|
	v_max3_f32 v7, v7, |v66|, |v67|
	v_max3_f32 v3, v7, |v60|, |v61|
	ds_bpermute_b32 v4, v205, v2
	v_max3_f32 v3, v3, |v62|, |v63|
	ds_bpermute_b32 v5, v205, v3
	v_lshlrev_b32_e32 v68, 4, v51
	v_cvt_pk_bf16_f32 v170, v74, v75
	s_waitcnt lgkmcnt(1)
	v_max_f32_e32 v4, v4, v4
	v_max_f32_e32 v2, v2, v4
	s_waitcnt lgkmcnt(0)
	v_max_f32_e32 v4, v5, v5
	v_max_f32_e32 v3, v3, v4
	v_mul_f32_e32 v2, 0x4138aa3b, v2
	v_mul_f32_e32 v2, v2, v3
	v_fmamk_f32 v19, v2, 0x3f828f5c, v215
	v_ashrrev_i32_e32 v4, 3, v51
	v_cmp_gt_f32_e32 vcc, s29, v19
	v_lshlrev_b32_e32 v2, 1, v69
	v_mov_b32_e32 v3, v1
	v_ashrrev_i32_e32 v5, 31, v4
	v_cndmask_b32_e64 v58, 0, 1, vcc
	v_add_co_u32_e32 v14, vcc, s30, v32
	v_lshl_add_u64 v[2:3], s[0:1], 0, v[2:3]
	v_lshlrev_b64 v[4:5], 10, v[4:5]
	v_addc_co_u32_e32 v15, vcc, 0, v33, vcc
	v_lshl_add_u64 v[10:11], v[2:3], 0, v[4:5]
	v_ashrrev_i32_e32 v4, 3, v31
	v_add_co_u32_e32 v16, vcc, s30, v34
	v_ashrrev_i32_e32 v5, 31, v4
	s_nop 0
	v_addc_co_u32_e32 v17, vcc, 0, v35, vcc
	v_lshlrev_b64 v[4:5], 10, v[4:5]
	v_add_co_u32_e32 v20, vcc, s30, v10
	v_lshl_add_u64 v[12:13], v[2:3], 0, v[4:5]
	s_nop 0
	v_addc_co_u32_e32 v21, vcc, 0, v11, vcc
	global_load_dwordx4 v[2:5], v[10:11], off offset:128
	global_load_dwordx4 v[6:9], v[12:13], off offset:128
	v_add_co_u32_e32 v32, vcc, s30, v12
	global_load_dwordx4 v[198:201], v[14:15], off
	global_load_dwordx4 v[194:197], v[16:17], off
	v_addc_co_u32_e32 v33, vcc, 0, v13, vcc
	global_load_dwordx4 v[186:189], v[20:21], off offset:128
	global_load_dwordx4 v[190:193], v[32:33], off offset:128
	v_cmp_lt_i32_e32 vcc, v229, v228
	v_readfirstlane_b32 s0, v58
	s_bitcmp1_b32 s0, 0
	v_cndmask_b32_e32 v10, v226, v229, vcc
	v_lshlrev_b32_e32 v206, 2, v10
	v_cmp_lt_i32_e32 vcc, v230, v228
	s_cselect_b64 s[0:1], -1, 0
	v_cvt_pk_bf16_f32 v171, v72, v73
	v_cvt_pk_bf16_f32 v172, v70, v71
	s_waitcnt vmcnt(9)
; #define MFMA32(a, b, c) __builtin_amdgcn_mfma_f32_32x32x16_bf16((a), (b), (c), 0, 0, 0)
; template <int DQK, int MODE, bool QN, bool KN> ...
;     ...
;   const int nsg = nkt >> 1;
;   auto tile_of = [&](int it) { return MODE == 2 ? (nkt - 1 - it) : it; };
;   auto stage_key0 = [&](int sg) { const int sc = sg < nsg ? sg : nsg - 1; return 128 * (MODE == 2 ? (nsg - 1 - sc) : sc); };
;   AT_GLOAD(rk0, rv0, 0)
;   AT_GLOAD(rk1, rv1, 1)
;   AT_SWRITE(rk0, rv0, 0)
;   __syncthreads();
;   auto compute = [&](int it, int bufi) {
;     const int kt = tile_of(it);
;     const int koff = (kt & 1) * 64;
;     const char* sK = smem + bufi * BUF + koff * KROW;
;     const char* sV = smem + bufi * BUF + KBYTES + koff * 64;
;     bool active = (MODE == 0) || (kt * 64 <= qwmax);
;     if (MODE == 2 && active) active = __builtin_amdgcn_ballot_w64(carry >= 1.17549435e-38f) != 0;
;     if (active) {
;       f32x16 sacc[2];
;       const float sinit = fixed_shift ? -sbound : 0.f;
; #pragma unroll
;       for (int kb = 0; kb < 2; ++kb) {
; #pragma unroll
;         for (int i = 0; i < 16; ++i) sacc[kb][i] = sinit;
; #pragma unroll
;         for (int s = 0; s < NS; ++s) {
;           const bf16x8 kf = *(const bf16x8*)(sK + (kb * 32 + r) * KROW + s * 32 + h * 16);
;           sacc[kb] = MFMA32(kf, qf[s], sacc[kb]);
;     ...
;         float tmax = -INFINITY;
; #pragma unroll
;         for (int kb = 0; kb < 2; ++kb)
; #pragma unroll
;           for (int i = 0; i < 16; ++i) {
;             tmax = fmaxf(tmax, sacc[kb][i]);
;           }
;         tmax = fmaxf(tmax, __shfl_xor(tmax, 32));
;         const float m_new = fmaxf(m_run, tmax);
;         const float alpha = __builtin_amdgcn_exp2f(m_run - m_new);
;         m_run = m_new;
	v_lshlrev_b32_e32 v40, 16, v22
	v_and_b32_e32 v41, 0xffff0000, v22
	s_waitcnt vmcnt(8)
	v_lshlrev_b32_e32 v54, 16, v26
	v_and_b32_e32 v55, 0xffff0000, v26
	v_lshlrev_b32_e32 v36, 16, v23
	v_and_b32_e32 v37, 0xffff0000, v23
	v_pk_mul_f32 v[22:23], v[40:41], v[40:41]
	v_lshlrev_b32_e32 v48, 16, v27
	v_and_b32_e32 v49, 0xffff0000, v27
	v_pk_mul_f32 v[26:27], v[54:55], v[54:55]
	v_pk_mul_f32 v[38:39], v[36:37], v[36:37]
	v_pk_mul_f32 v[52:53], v[48:49], v[48:49]
	v_mov_b32_e32 v56, v26
	v_mov_b32_e32 v57, v22
	v_mov_b32_e32 v22, v27
	v_lshlrev_b32_e32 v12, 16, v24
	v_and_b32_e32 v13, 0xffff0000, v24
	v_lshlrev_b32_e32 v46, 16, v28
	v_and_b32_e32 v47, 0xffff0000, v28
	v_pk_add_f32 v[22:23], v[56:57], v[22:23]
	v_mov_b32_e32 v26, v52
	v_mov_b32_e32 v27, v38
	v_lshlrev_b32_e32 v34, 16, v25
	v_and_b32_e32 v35, 0xffff0000, v25
	v_pk_mul_f32 v[24:25], v[12:13], v[12:13]
	v_lshlrev_b32_e32 v42, 16, v29
	v_and_b32_e32 v43, 0xffff0000, v29
	v_pk_mul_f32 v[28:29], v[46:47], v[46:47]
	v_pk_add_f32 v[22:23], v[26:27], v[22:23]
	v_mov_b32_e32 v38, v53
	v_pk_add_f32 v[22:23], v[38:39], v[22:23]
	v_mov_b32_e32 v26, v28
	v_mov_b32_e32 v27, v24
	v_pk_mul_f32 v[10:11], v[34:35], v[34:35]
	v_pk_mul_f32 v[44:45], v[42:43], v[42:43]
	v_pk_add_f32 v[22:23], v[26:27], v[22:23]
	v_mov_b32_e32 v24, v29
	v_pk_add_f32 v[22:23], v[24:25], v[22:23]
	v_mov_b32_e32 v24, v44
	v_mov_b32_e32 v25, v10
	v_pk_add_f32 v[22:23], v[24:25], v[22:23]
	v_mov_b32_e32 v10, v45
	v_pk_add_f32 v[10:11], v[10:11], v[22:23]
	ds_bpermute_b32 v23, v206, v11
	ds_bpermute_b32 v22, v206, v10
	v_cndmask_b32_e32 v24, v226, v230, vcc
	v_lshlrev_b32_e32 v208, 2, v24
	v_cmp_lt_i32_e32 vcc, v231, v228
	s_waitcnt lgkmcnt(0)
	v_pk_add_f32 v[10:11], v[10:11], v[22:23]
	ds_bpermute_b32 v23, v208, v11
	ds_bpermute_b32 v22, v208, v10
	v_cndmask_b32_e32 v24, v226, v231, vcc
	v_lshlrev_b32_e32 v209, 2, v24
	v_mul_lo_u32 v24, v30, s31
	v_add_u32_e32 v24, 0x110, v24
	s_waitcnt lgkmcnt(0)
	v_pk_add_f32 v[10:11], v[10:11], v[22:23]
	ds_bpermute_b32 v23, v209, v11
	ds_bpermute_b32 v22, v209, v10
	s_waitcnt lgkmcnt(0)
	v_pk_add_f32 v[10:11], v[10:11], v[22:23]
	s_nop 0
	v_pk_fma_f32 v[22:23], v[10:11], s[8:9], v[214:215] op_sel_hi:[1,0,0]
	v_lshlrev_b32_e32 v11, 7, v30
	v_mul_f32_e32 v10, 0x4b800000, v23
	v_cmp_gt_f32_e32 vcc, s28, v23
	v_sub_u32_e32 v11, v68, v11
	v_add_u32_e32 v207, v24, v11
	v_cndmask_b32_e32 v10, v23, v10, vcc
	v_rsq_f32_e32 v10, v10
	s_nop 0
	v_mul_f32_e32 v11, 0x45800000, v10
	v_cndmask_b32_e32 v24, v10, v11, vcc
	v_pk_mul_f32 v[12:13], v[24:25], v[12:13] op_sel_hi:[0,1]
	s_waitcnt vmcnt(7)
	v_pk_mul_f32 v[12:13], v[146:147], v[12:13]
	v_pk_mul_f32 v[10:11], v[24:25], v[40:41] op_sel_hi:[0,1]
	v_pk_mul_f32 v[26:27], v[24:25], v[36:37] op_sel_hi:[0,1]
	v_cvt_pk_bf16_f32 v12, v12, v13
	v_mul_f32_e32 v13, 0x4b800000, v22
	v_cmp_gt_f32_e32 vcc, s28, v22
	s_waitcnt vmcnt(6)
	v_pk_mul_f32 v[10:11], v[150:151], v[10:11]
	v_pk_mul_f32 v[26:27], v[152:153], v[26:27]
	v_cndmask_b32_e32 v13, v22, v13, vcc
	v_cvt_pk_bf16_f32 v10, v10, v11
	v_cvt_pk_bf16_f32 v11, v26, v27
	v_rsq_f32_e32 v26, v13
	v_pk_mul_f32 v[24:25], v[24:25], v[34:35] op_sel_hi:[0,1]
	v_pk_mul_f32 v[22:23], v[148:149], v[24:25]
	s_nop 0
	v_cvt_pk_bf16_f32 v13, v22, v23
	ds_write_b128 v207, v[10:13]
	v_mul_f32_e32 v10, 0x45800000, v26
	v_cndmask_b32_e32 v22, v26, v10, vcc
	v_pk_mul_f32 v[10:11], v[22:23], v[54:55] op_sel_hi:[0,1]
	v_pk_mul_f32 v[12:13], v[22:23], v[48:49] op_sel_hi:[0,1]
	v_pk_mul_f32 v[10:11], v[150:151], v[10:11]
	v_pk_mul_f32 v[12:13], v[152:153], v[12:13]
	v_cvt_pk_bf16_f32 v10, v10, v11
	v_cvt_pk_bf16_f32 v11, v12, v13
	v_pk_mul_f32 v[12:13], v[22:23], v[46:47] op_sel_hi:[0,1]
	v_pk_mul_f32 v[22:23], v[22:23], v[42:43] op_sel_hi:[0,1]
	v_pk_mul_f32 v[12:13], v[146:147], v[12:13]
	v_pk_mul_f32 v[22:23], v[148:149], v[22:23]
	v_cvt_pk_bf16_f32 v12, v12, v13
	v_cvt_pk_bf16_f32 v13, v22, v23
	v_mul_lo_u32 v22, v18, s31
	v_lshlrev_b32_e32 v18, 7, v18
	v_lshlrev_b32_e32 v23, 4, v31
	v_add_u32_e32 v22, 0x110, v22
	v_sub_u32_e32 v18, v23, v18
	v_add_u32_e32 v210, v22, v18
	ds_write_b128 v210, v[10:13]
	v_lshlrev_b32_e32 v10, 11, v51
	v_and_b32_e32 v10, 0x2000, v10
	v_and_b32_e32 v11, 48, v68
	v_add3_u32 v10, s34, v10, v11
	v_and_b32_e32 v11, 0xffffffc0, v50
	v_add_u32_e32 v211, v10, v11
	s_waitcnt vmcnt(5)
	ds_write_b128 v211, v[2:5] offset:18432
	s_waitcnt vmcnt(4)
	ds_write_b128 v211, v[6:9] offset:22528
	v_cndmask_b32_e64 v2, 0, -v19, s[0:1]
	v_mad_u32_u24 v26, v98, s31, v0
	s_waitcnt lgkmcnt(0)
	s_barrier
	global_load_dwordx4 v[166:169], v[14:15], off
	global_load_dwordx4 v[162:165], v[16:17], off
	global_load_dwordx4 v[154:157], v[20:21], off offset:128
	global_load_dwordx4 v[158:161], v[32:33], off offset:128
	v_mov_b32_e32 v3, v2
	v_mov_b32_e32 v4, v2
	v_mov_b32_e32 v5, v2
	v_mov_b32_e32 v6, v2
	v_mov_b32_e32 v7, v2
	v_mov_b32_e32 v8, v2
	v_mov_b32_e32 v9, v2
	v_mov_b32_e32 v10, v2
	v_mov_b32_e32 v11, v2
	v_mov_b32_e32 v12, v2
	v_mov_b32_e32 v13, v2
	v_mov_b32_e32 v14, v2
	v_mov_b32_e32 v15, v2
	v_mov_b32_e32 v16, v2
	v_mov_b32_e32 v17, v2
	ds_read_b128 v[18:21], v26
	ds_read_b128 v[22:25], v26 offset:32
	s_and_b64 vcc, exec, s[0:1]
	s_waitcnt lgkmcnt(1)
	v_mfma_f32_32x32x16_bf16 v[52:67], v[18:21], v[174:177], v[2:17]
	s_waitcnt lgkmcnt(0)
	v_mfma_f32_32x32x16_bf16 v[52:67], v[22:25], v[182:185], v[52:67]
	ds_read_b128 v[18:21], v26 offset:64
	ds_read_b128 v[22:25], v26 offset:96
	s_waitcnt lgkmcnt(1)
	v_mfma_f32_32x32x16_bf16 v[52:67], v[18:21], v[178:181], v[52:67]
	s_waitcnt lgkmcnt(0)
	v_mfma_f32_32x32x16_bf16 v[52:67], v[22:25], v[170:173], v[52:67]
	ds_read_b128 v[18:21], v26 offset:4608
	ds_read_b128 v[22:25], v26 offset:4640
	s_waitcnt lgkmcnt(1)
	v_mfma_f32_32x32x16_bf16 v[34:49], v[18:21], v[174:177], v[2:17]
	ds_read_b128 v[18:21], v26 offset:4672
	ds_read_b128 v[70:73], v26 offset:4704
	s_waitcnt lgkmcnt(2)
	v_mfma_f32_32x32x16_bf16 v[34:49], v[22:25], v[182:185], v[34:49]
	s_waitcnt lgkmcnt(1)
	v_mfma_f32_32x32x16_bf16 v[34:49], v[18:21], v[178:181], v[34:49]
	s_waitcnt lgkmcnt(0)
	v_mfma_f32_32x32x16_bf16 v[34:49], v[70:73], v[170:173], v[34:49]
	s_cbranch_vccnz .LBB0_1173
	v_max3_f32 v18, v52, s35, v53
	v_max3_f32 v18, v18, v54, v55
	v_max3_f32 v18, v18, v56, v57
	v_max3_f32 v18, v18, v58, v59
	v_max3_f32 v18, v18, v60, v61
	v_max3_f32 v18, v18, v62, v63
	v_max3_f32 v18, v18, v64, v65
	v_max3_f32 v18, v18, v66, v67
	s_nop 2
	v_max3_f32 v18, v18, v34, v35
	v_max3_f32 v18, v18, v36, v37
	v_max3_f32 v18, v18, v38, v39
	v_max3_f32 v18, v18, v40, v41
	v_max3_f32 v18, v18, v42, v43
	v_max3_f32 v18, v18, v44, v45
	v_max3_f32 v18, v18, v46, v47
	v_max3_f32 v18, v18, v48, v49
	ds_bpermute_b32 v19, v205, v18
	v_mov_b32_e32 v50, 0
	s_waitcnt lgkmcnt(0)
	v_max3_f32 v218, v18, v19, s35
	v_sub_f32_e32 v18, 0xff800000, v218
	v_exp_f32_e32 v69, v18
	s_nop 0
	v_cmp_neq_f32_e32 vcc, 1.0, v69
	s_cbranch_vccz .LBB0_1172
	v_mul_f32_e32 v50, 0, v69

; __global__ void __launch_bounds__(NTHREADS, 2) fwd_megakernel(Params p) {
;   extern __shared__ __attribute__((aligned(16))) char smem[];
	.amdhsa_kernel _Z14fwd_megakernel6Params
		.amdhsa_group_segment_fixed_size 272
		.amdhsa_private_segment_fixed_size 0
		.amdhsa_kernarg_size 432
		.amdhsa_user_sgpr_count 2
		.amdhsa_user_sgpr_dispatch_ptr 0
		.amdhsa_user_sgpr_queue_ptr 0
		.amdhsa_user_sgpr_kernarg_segment_ptr 1
		.amdhsa_user_sgpr_dispatch_id 0
		.amdhsa_user_sgpr_kernarg_preload_length 0
		.amdhsa_user_sgpr_kernarg_preload_offset 0
		.amdhsa_user_sgpr_private_segment_size 0
		.amdhsa_uses_dynamic_stack 0
		.amdhsa_enable_private_segment 0
		.amdhsa_system_sgpr_workgroup_id_x 1
		.amdhsa_system_sgpr_workgroup_id_y 0
		.amdhsa_system_sgpr_workgroup_id_z 0
		.amdhsa_system_sgpr_workgroup_info 0
		.amdhsa_system_vgpr_workitem_id 2
		.amdhsa_next_free_vgpr 256
		.amdhsa_next_free_sgpr 100
		.amdhsa_accum_offset 256
		.amdhsa_reserve_vcc 1
		.amdhsa_float_round_mode_32 0
		.amdhsa_float_round_mode_16_64 0
		.amdhsa_float_denorm_mode_32 3
		.amdhsa_float_denorm_mode_16_64 3
		.amdhsa_dx10_clamp 1
		.amdhsa_ieee_mode 1
		.amdhsa_fp16_overflow 0
		.amdhsa_tg_split 0
		.amdhsa_exception_fp_ieee_invalid_op 0
		.amdhsa_exception_fp_denorm_src 0
		.amdhsa_exception_fp_ieee_div_zero 0
		.amdhsa_exception_fp_ieee_overflow 0
		.amdhsa_exception_fp_ieee_underflow 0
		.amdhsa_exception_fp_ieee_inexact 0
		.amdhsa_exception_int_div_zero 0
	.end_amdhsa_kernel

; __global__ void __launch_bounds__(NTHREADS, 2) fwd_megakernel(Params p) {
;   extern __shared__ __attribute__((aligned(16))) char smem[];
amdhsa.kernels:
  - .agpr_count:     0
    .args:
      - .offset:         0
        .size:           176
        .value_kind:     by_value
      - .offset:         176
        .size:           4
        .value_kind:     hidden_block_count_x
      - .offset:         180
        .size:           4
        .value_kind:     hidden_block_count_y
      - .offset:         184
        .size:           4
        .value_kind:     hidden_block_count_z
      - .offset:         188
        .size:           2
        .value_kind:     hidden_group_size_x
      - .offset:         190
        .size:           2
        .value_kind:     hidden_group_size_y
      - .offset:         192
        .size:           2
        .value_kind:     hidden_group_size_z
      - .offset:         194
        .size:           2
        .value_kind:     hidden_remainder_x
      - .offset:         196
        .size:           2
        .value_kind:     hidden_remainder_y
      - .offset:         198
        .size:           2
        .value_kind:     hidden_remainder_z
      - .offset:         216
        .size:           8
        .value_kind:     hidden_global_offset_x
      - .offset:         224
        .size:           8
        .value_kind:     hidden_global_offset_y
      - .offset:         232
        .size:           8
        .value_kind:     hidden_global_offset_z
      - .offset:         240
        .size:           2
        .value_kind:     hidden_grid_dims
      - .offset:         264
        .size:           8
        .value_kind:     hidden_multigrid_sync_arg
      - .offset:         296
        .size:           4
        .value_kind:     hidden_dynamic_lds_size
    .group_segment_fixed_size: 272
    .kernarg_segment_align: 8
    .kernarg_segment_size: 432
    .language:       OpenCL C
    .language_version:
      - 2
      - 0
    .max_flat_workgroup_size: 512
    .name:           _Z14fwd_megakernel6Params
    .private_segment_fixed_size: 0
    .sgpr_count:     106
    .sgpr_spill_count: 34
    .symbol:         _Z14fwd_megakernel6Params.kd
    .uniform_work_group_size: 1
    .uses_dynamic_stack: false
    .vgpr_count:     256
    .vgpr_spill_count: 0
    .wavefront_size: 64
